# back-edge rotation in all six GEMM K-loops: loop counter and pointer SALU updates moved in front of the loop-closing s_barrier
# baseline (speedup 1.0000x reference)
; #define PG8_STAGE(bufoff, gbase, voff) do { _Pragma("unroll") for (int _i = 0; _i < 2; ++_i) \
;         __builtin_amdgcn_global_load_lds((const unsigned*)((const char*)(gbase) + (voff)[_i]), (PG8_LAS unsigned*)(lds + (bufoff) + ldsw + _i * 8192), 16, 0, 0); } while (0)
; #define PG8_LDA(dst, b, h) do { _Pragma("unroll") for (int m = 0; m < 4; ++m) _Pragma("unroll") for (int k = 0; k < 2; ++k) dst[m][k] = *(const PG8_LAS bf16x8*)(lds + PG8_SA(b, h) + aoff + m * 2048 + k * 1024); } while (0)
; #define PG8_LDB(dst, b, h) do { _Pragma("unroll") for (int n = 0; n < 2; ++n) _Pragma("unroll") for (int k = 0; k < 2; ++k) dst[n][k] = *(const PG8_LAS bf16x8*)(lds + PG8_SB(b, h) + boff + n * 2048 + k * 1024); } while (0)
; #define PG8_MMA(ai, bj, At, Bt) do { __builtin_amdgcn_s_setprio(1); _Pragma("unroll") for (int m = 0; m < 4; ++m) _Pragma("unroll") for (int n = 0; n < 2; ++n) _Pragma("unroll") for (int k = 0; k < 2; ++k) \
;         acc[ai][bj][m][n] = __builtin_amdgcn_mfma_f32_16x16x32_bf16(Bt[n][k], At[m][k], acc[ai][bj][m][n], 0, 0, 0); __builtin_amdgcn_s_setprio(0); } while (0)
; #define PG8_WAIT_V(n) asm volatile("s_waitcnt vmcnt(" #n ")" ::: "memory")
; #define PG8_WAIT_L(n) asm volatile("s_waitcnt lgkmcnt(" #n ")" ::: "memory")
; template <class Epi, class Sched, bool ALIGN_EPI = false, bool SP2 = false>
; __device__ __forceinline__ void gemm_phase(PG8_LAS unsigned char* lds, const Gemm g, const Sched& S, const Epi& E) {
;     ...
;             const bool last = (t == nt - 2);
;             const char* a1 = cA + (size_t)(t + 1) * kstep;
;             const char* a2 = last ? nA : cA + (size_t)(t + 2) * kstep; const char* b2 = last ? nB : cB + (size_t)(t + 2) * kstep;
;             const char* a3 = a2 + kstep; const char* b3 = b2 + kstep;
;             if (last && has_next) S.a_ready(nxt);
;             if constexpr (SP2) {
;             PG8_LDB(B0, 0, 0); PG8_LDB(B1, 0, 1); PG8_SCHED; PG8_LDA(At, 0, 0); PG8_STAGE(PG8_SA(1, 1), a1 + hstep, voffA);
;             PG8_WAIT_V(8); PG8_WAIT_L(0); PG8_BAR; PG8_MMA(0, 0, At, B0); PG8_MMA(0, 1, At, B1); PG8_BAR; PG8_SCHED;
;             PG8_LDA(At, 0, 1); PG8_STAGE(PG8_SB(0, 0), b2, voffB); PG8_STAGE(PG8_SB(0, 1), b2 + hstep, voffB); PG8_STAGE(PG8_SA(0, 0), a2, voffA);
;             PG8_WAIT_V(8); PG8_WAIT_L(0); PG8_BAR; PG8_MMA(1, 0, At, B0); PG8_MMA(1, 1, At, B1); PG8_BAR; PG8_SCHED;
.LBB0_323:
	s_add_u32 s2, s16, 0xfff80080
	s_addc_u32 s3, s17, -1
	s_add_i32 s36, 0, 0x10000
	s_cmp_eq_u32 s35, 28
	s_cselect_b32 s19, s11, s3
	s_cselect_b32 s18, s30, s2
	s_cselect_b32 s3, s9, s34
	s_cselect_b32 s2, s31, s33
	s_add_i32 s38, 0, 0x14000
	v_add_u32_e32 v156, s36, v145
	v_add_u32_e32 v178, s38, v145
	ds_read_b128 v[140:143], v156
	ds_read_b128 v[148:151], v156 offset:1024
	ds_read_b128 v[152:155], v156 offset:2048
	ds_read_b128 v[156:159], v156 offset:3072
	ds_read_b128 v[160:163], v178
	ds_read_b128 v[170:173], v178 offset:1024
	ds_read_b128 v[174:177], v178 offset:2048
	ds_read_b128 v[178:181], v178 offset:3072
	v_lshl_add_u64 v[234:235], s[16:17], 0, v[136:137]
	s_add_i32 m0, s21, 0xc000
	ds_read_b128 v[182:185], v147
	ds_read_b128 v[186:189], v147 offset:1024
	ds_read_b128 v[190:193], v147 offset:2048
	ds_read_b128 v[194:197], v147 offset:3072
	ds_read_b128 v[222:225], v147 offset:4096
	ds_read_b128 v[226:229], v147 offset:5120
	ds_read_b128 v[230:233], v147 offset:6144
	ds_read_b128 v[240:243], v147 offset:7168
	global_load_lds_dwordx4 v[234:235], off
	v_lshl_add_u64 v[234:235], s[16:17], 0, v[138:139]
	s_add_i32 m0, s21, 0xe000
	s_nop 0
	global_load_lds_dwordx4 v[234:235], off
	s_waitcnt vmcnt(8)
	s_waitcnt lgkmcnt(0)
	s_barrier
	s_setprio 1
	s_waitcnt lgkmcnt(0)
	v_mfma_f32_16x16x32_bf16 v[126:129], v[140:143], v[182:185], v[126:129]
	v_mfma_f32_16x16x32_bf16 v[122:125], v[152:155], v[182:185], v[122:125]
	v_mfma_f32_16x16x32_bf16 v[118:121], v[140:143], v[190:193], v[118:121]
	v_mfma_f32_16x16x32_bf16 v[110:113], v[152:155], v[190:193], v[110:113]
	v_mfma_f32_16x16x32_bf16 v[102:105], v[140:143], v[222:225], v[102:105]
	v_mfma_f32_16x16x32_bf16 v[94:97], v[152:155], v[222:225], v[94:97]
	v_mfma_f32_16x16x32_bf16 v[86:89], v[140:143], v[230:233], v[86:89]
	v_mfma_f32_16x16x32_bf16 v[78:81], v[152:155], v[230:233], v[78:81]
	v_mfma_f32_16x16x32_bf16 v[126:129], v[148:151], v[186:189], v[126:129]
	v_mfma_f32_16x16x32_bf16 v[122:125], v[156:159], v[186:189], v[122:125]
	v_mfma_f32_16x16x32_bf16 v[118:121], v[148:151], v[194:197], v[118:121]
	v_mfma_f32_16x16x32_bf16 v[110:113], v[156:159], v[194:197], v[110:113]
	v_mfma_f32_16x16x32_bf16 v[102:105], v[148:151], v[226:229], v[102:105]
	v_mfma_f32_16x16x32_bf16 v[94:97], v[156:159], v[226:229], v[94:97]
	v_mfma_f32_16x16x32_bf16 v[86:89], v[148:151], v[240:243], v[86:89]
	v_mfma_f32_16x16x32_bf16 v[78:81], v[156:159], v[240:243], v[78:81]
	s_setprio 0
	s_setprio 1
	v_mfma_f32_16x16x32_bf16 v[114:117], v[160:163], v[182:185], v[114:117]
	v_mfma_f32_16x16x32_bf16 v[106:109], v[174:177], v[182:185], v[106:109]
	v_mfma_f32_16x16x32_bf16 v[98:101], v[160:163], v[190:193], v[98:101]
	v_mfma_f32_16x16x32_bf16 v[90:93], v[174:177], v[190:193], v[90:93]
	v_mfma_f32_16x16x32_bf16 v[82:85], v[160:163], v[222:225], v[82:85]
	v_mfma_f32_16x16x32_bf16 v[74:77], v[174:177], v[222:225], v[74:77]
	v_mfma_f32_16x16x32_bf16 v[70:73], v[160:163], v[230:233], v[70:73]
	v_mfma_f32_16x16x32_bf16 v[66:69], v[174:177], v[230:233], v[66:69]
	v_mfma_f32_16x16x32_bf16 v[114:117], v[170:173], v[186:189], v[114:117]
	v_mfma_f32_16x16x32_bf16 v[106:109], v[178:181], v[186:189], v[106:109]
	v_mfma_f32_16x16x32_bf16 v[98:101], v[170:173], v[194:197], v[98:101]
	v_mfma_f32_16x16x32_bf16 v[90:93], v[178:181], v[194:197], v[90:93]
	v_mfma_f32_16x16x32_bf16 v[82:85], v[170:173], v[226:229], v[82:85]
	v_mfma_f32_16x16x32_bf16 v[74:77], v[178:181], v[226:229], v[74:77]
	v_mfma_f32_16x16x32_bf16 v[70:73], v[170:173], v[240:243], v[70:73]
	v_mfma_f32_16x16x32_bf16 v[66:69], v[178:181], v[240:243], v[66:69]
	s_setprio 0
	s_barrier
	s_add_i32 s36, s36, s20
	v_lshl_add_u64 v[234:235], s[2:3], 0, v[0:1]
	s_mov_b32 m0, s36
	ds_read_b128 v[182:185], v147 offset:16384
	ds_read_b128 v[186:189], v147 offset:17408
	ds_read_b128 v[190:193], v147 offset:18432
	ds_read_b128 v[194:197], v147 offset:19456
	ds_read_b128 v[222:225], v147 offset:20480
	ds_read_b128 v[226:229], v147 offset:21504
	ds_read_b128 v[230:233], v147 offset:22528
	ds_read_b128 v[240:243], v147 offset:23552
	global_load_lds_dwordx4 v[234:235], off
	s_add_i32 m0, s36, 0x2000
	s_add_u32 s36, s2, 0x80000
	v_lshl_add_u64 v[244:245], s[2:3], 0, v[130:131]
	s_addc_u32 s37, s3, 0
	s_add_i32 s38, s38, s20
	global_load_lds_dwordx4 v[244:245], off
	v_lshl_add_u64 v[246:247], s[36:37], 0, v[0:1]
	s_mov_b32 m0, s38
	v_lshl_add_u64 v[248:249], s[18:19], 0, v[132:133]
	global_load_lds_dwordx4 v[246:247], off
	v_lshl_add_u64 v[246:247], s[36:37], 0, v[130:131]
	s_add_i32 m0, s38, 0x2000
	s_nop 0
	global_load_lds_dwordx4 v[246:247], off
	v_lshl_add_u64 v[246:247], s[18:19], 0, v[134:135]
	s_mov_b32 m0, s21
	s_nop 0
	global_load_lds_dwordx4 v[246:247], off
	s_mov_b32 m0, s22
	s_nop 0
	global_load_lds_dwordx4 v[248:249], off
	s_waitcnt vmcnt(8)
	s_waitcnt lgkmcnt(0)
	s_barrier
; #define PG8_STAGE(bufoff, gbase, voff) do { _Pragma("unroll") for (int _i = 0; _i < 2; ++_i) \
;         __builtin_amdgcn_global_load_lds((const unsigned*)((const char*)(gbase) + (voff)[_i]), (PG8_LAS unsigned*)(lds + (bufoff) + ldsw + _i * 8192), 16, 0, 0); } while (0)
; #define PG8_LDA(dst, b, h) do { _Pragma("unroll") for (int m = 0; m < 4; ++m) _Pragma("unroll") for (int k = 0; k < 2; ++k) dst[m][k] = *(const PG8_LAS bf16x8*)(lds + PG8_SA(b, h) + aoff + m * 2048 + k * 1024); } while (0)
; #define PG8_LDB(dst, b, h) do { _Pragma("unroll") for (int n = 0; n < 2; ++n) _Pragma("unroll") for (int k = 0; k < 2; ++k) dst[n][k] = *(const PG8_LAS bf16x8*)(lds + PG8_SB(b, h) + boff + n * 2048 + k * 1024); } while (0)
; #define PG8_MMA(ai, bj, At, Bt) do { __builtin_amdgcn_s_setprio(1); _Pragma("unroll") for (int m = 0; m < 4; ++m) _Pragma("unroll") for (int n = 0; n < 2; ++n) _Pragma("unroll") for (int k = 0; k < 2; ++k) \
;         acc[ai][bj][m][n] = __builtin_amdgcn_mfma_f32_16x16x32_bf16(Bt[n][k], At[m][k], acc[ai][bj][m][n], 0, 0, 0); __builtin_amdgcn_s_setprio(0); } while (0)
; #define PG8_WAIT_V(n) asm volatile("s_waitcnt vmcnt(" #n ")" ::: "memory")
; #define PG8_WAIT_L(n) asm volatile("s_waitcnt lgkmcnt(" #n ")" ::: "memory")
; #define PG8_BAR __builtin_amdgcn_s_barrier()
; #define PG8_SCHED __builtin_amdgcn_sched_barrier(0)
; template <class Epi, class Sched, bool ALIGN_EPI = false, bool SP2 = false>
; __device__ __forceinline__ void gemm_phase(PG8_LAS unsigned char* lds, const Gemm g, const Sched& S, const Epi& E) {
;     ...
;             PG8_WAIT_V(8); PG8_WAIT_L(0); PG8_BAR; PG8_MMA(1, 0, At, B0); PG8_MMA(1, 1, At, B1); PG8_BAR; PG8_SCHED;
;             PG8_LDB(B0, 1, 0); PG8_LDB(B1, 1, 1); PG8_SCHED; PG8_LDA(At, 1, 0); PG8_STAGE(PG8_SA(0, 1), a2 + hstep, voffA);
;             PG8_WAIT_V(8); PG8_WAIT_L(0); PG8_BAR; PG8_MMA(0, 0, At, B0); PG8_MMA(0, 1, At, B1); PG8_BAR; PG8_SCHED;
	s_setprio 1
	s_waitcnt lgkmcnt(0)
	v_mfma_f32_16x16x32_bf16 v[62:65], v[140:143], v[182:185], v[62:65]
	v_mfma_f32_16x16x32_bf16 v[58:61], v[152:155], v[182:185], v[58:61]
	v_mfma_f32_16x16x32_bf16 v[54:57], v[140:143], v[190:193], v[54:57]
	v_mfma_f32_16x16x32_bf16 v[46:49], v[152:155], v[190:193], v[46:49]
	v_mfma_f32_16x16x32_bf16 v[38:41], v[140:143], v[222:225], v[38:41]
	v_mfma_f32_16x16x32_bf16 v[30:33], v[152:155], v[222:225], v[30:33]
	v_mfma_f32_16x16x32_bf16 v[22:25], v[140:143], v[230:233], v[22:25]
	v_mfma_f32_16x16x32_bf16 v[14:17], v[152:155], v[230:233], v[14:17]
	v_mfma_f32_16x16x32_bf16 v[62:65], v[148:151], v[186:189], v[62:65]
	v_mfma_f32_16x16x32_bf16 v[58:61], v[156:159], v[186:189], v[58:61]
	v_mfma_f32_16x16x32_bf16 v[54:57], v[148:151], v[194:197], v[54:57]
	v_mfma_f32_16x16x32_bf16 v[46:49], v[156:159], v[194:197], v[46:49]
	v_mfma_f32_16x16x32_bf16 v[38:41], v[148:151], v[226:229], v[38:41]
	v_mfma_f32_16x16x32_bf16 v[30:33], v[156:159], v[226:229], v[30:33]
	v_mfma_f32_16x16x32_bf16 v[22:25], v[148:151], v[240:243], v[22:25]
	v_mfma_f32_16x16x32_bf16 v[14:17], v[156:159], v[240:243], v[14:17]
	s_setprio 0
	s_setprio 1
	v_mfma_f32_16x16x32_bf16 v[50:53], v[160:163], v[182:185], v[50:53]
	v_mfma_f32_16x16x32_bf16 v[42:45], v[174:177], v[182:185], v[42:45]
	v_mfma_f32_16x16x32_bf16 v[34:37], v[160:163], v[190:193], v[34:37]
	v_mfma_f32_16x16x32_bf16 v[26:29], v[174:177], v[190:193], v[26:29]
	v_mfma_f32_16x16x32_bf16 v[18:21], v[160:163], v[222:225], v[18:21]
	v_mfma_f32_16x16x32_bf16 v[10:13], v[174:177], v[222:225], v[10:13]
	v_mfma_f32_16x16x32_bf16 v[6:9], v[160:163], v[230:233], v[6:9]
	v_mfma_f32_16x16x32_bf16 v[2:5], v[174:177], v[230:233], v[2:5]
	v_mfma_f32_16x16x32_bf16 v[50:53], v[170:173], v[186:189], v[50:53]
	v_mfma_f32_16x16x32_bf16 v[42:45], v[178:181], v[186:189], v[42:45]
	v_mfma_f32_16x16x32_bf16 v[34:37], v[170:173], v[194:197], v[34:37]
	v_mfma_f32_16x16x32_bf16 v[26:29], v[178:181], v[194:197], v[26:29]
	v_mfma_f32_16x16x32_bf16 v[18:21], v[170:173], v[226:229], v[18:21]
	v_mfma_f32_16x16x32_bf16 v[10:13], v[178:181], v[226:229], v[10:13]
	v_mfma_f32_16x16x32_bf16 v[6:9], v[170:173], v[240:243], v[6:9]
	v_mfma_f32_16x16x32_bf16 v[2:5], v[178:181], v[240:243], v[2:5]
	s_setprio 0
	s_barrier
	s_add_i32 s36, 0, 0x18000
	s_add_i32 s37, 0, 0x1c000
	v_add_u32_e32 v156, s36, v145
	v_add_u32_e32 v178, s37, v145
	ds_read_b128 v[140:143], v156
	ds_read_b128 v[148:151], v156 offset:1024
	ds_read_b128 v[152:155], v156 offset:2048
	ds_read_b128 v[156:159], v156 offset:3072
	ds_read_b128 v[160:163], v178
	ds_read_b128 v[170:173], v178 offset:1024
	ds_read_b128 v[174:177], v178 offset:2048
	ds_read_b128 v[178:181], v178 offset:3072
	s_add_u32 s18, s18, 0x80000
	s_addc_u32 s19, s19, 0
	s_mov_b32 m0, s23
	v_lshl_add_u64 v[204:205], s[18:19], 0, v[134:135]
	ds_read_b128 v[182:185], v147 offset:32768
	ds_read_b128 v[186:189], v147 offset:33792
	ds_read_b128 v[190:193], v147 offset:34816
	ds_read_b128 v[194:197], v147 offset:35840
	ds_read_b128 v[222:225], v147 offset:36864
	ds_read_b128 v[226:229], v147 offset:37888
	ds_read_b128 v[230:233], v147 offset:38912
	ds_read_b128 v[240:243], v147 offset:39936
	global_load_lds_dwordx4 v[204:205], off
	v_lshl_add_u64 v[204:205], s[18:19], 0, v[132:133]
	s_mov_b32 m0, s24
	s_nop 0
	global_load_lds_dwordx4 v[204:205], off
	s_waitcnt vmcnt(8)
	s_waitcnt lgkmcnt(0)
	s_barrier
	s_setprio 1
	s_waitcnt lgkmcnt(0)
	v_mfma_f32_16x16x32_bf16 v[126:129], v[140:143], v[182:185], v[126:129]
	v_mfma_f32_16x16x32_bf16 v[122:125], v[152:155], v[182:185], v[122:125]
	v_mfma_f32_16x16x32_bf16 v[118:121], v[140:143], v[190:193], v[118:121]
	v_mfma_f32_16x16x32_bf16 v[110:113], v[152:155], v[190:193], v[110:113]
	v_mfma_f32_16x16x32_bf16 v[102:105], v[140:143], v[222:225], v[102:105]
	v_mfma_f32_16x16x32_bf16 v[94:97], v[152:155], v[222:225], v[94:97]
	v_mfma_f32_16x16x32_bf16 v[86:89], v[140:143], v[230:233], v[86:89]
	v_mfma_f32_16x16x32_bf16 v[78:81], v[152:155], v[230:233], v[78:81]
	v_mfma_f32_16x16x32_bf16 v[126:129], v[148:151], v[186:189], v[126:129]
	v_mfma_f32_16x16x32_bf16 v[122:125], v[156:159], v[186:189], v[122:125]
	v_mfma_f32_16x16x32_bf16 v[118:121], v[148:151], v[194:197], v[118:121]
	v_mfma_f32_16x16x32_bf16 v[110:113], v[156:159], v[194:197], v[110:113]
	v_mfma_f32_16x16x32_bf16 v[102:105], v[148:151], v[226:229], v[102:105]
	v_mfma_f32_16x16x32_bf16 v[94:97], v[156:159], v[226:229], v[94:97]
	v_mfma_f32_16x16x32_bf16 v[86:89], v[148:151], v[240:243], v[86:89]
	v_mfma_f32_16x16x32_bf16 v[78:81], v[156:159], v[240:243], v[78:81]
	s_setprio 0
	s_setprio 1
	v_mfma_f32_16x16x32_bf16 v[114:117], v[160:163], v[182:185], v[114:117]
	v_mfma_f32_16x16x32_bf16 v[106:109], v[174:177], v[182:185], v[106:109]
	v_mfma_f32_16x16x32_bf16 v[98:101], v[160:163], v[190:193], v[98:101]
	v_mfma_f32_16x16x32_bf16 v[90:93], v[174:177], v[190:193], v[90:93]
	v_mfma_f32_16x16x32_bf16 v[82:85], v[160:163], v[222:225], v[82:85]
	v_mfma_f32_16x16x32_bf16 v[74:77], v[174:177], v[222:225], v[74:77]
	v_mfma_f32_16x16x32_bf16 v[70:73], v[160:163], v[230:233], v[70:73]
	v_mfma_f32_16x16x32_bf16 v[66:69], v[174:177], v[230:233], v[66:69]
	v_mfma_f32_16x16x32_bf16 v[114:117], v[170:173], v[186:189], v[114:117]
	v_mfma_f32_16x16x32_bf16 v[106:109], v[178:181], v[186:189], v[106:109]
	v_mfma_f32_16x16x32_bf16 v[98:101], v[170:173], v[194:197], v[98:101]
	v_mfma_f32_16x16x32_bf16 v[90:93], v[178:181], v[194:197], v[90:93]
	v_mfma_f32_16x16x32_bf16 v[82:85], v[170:173], v[226:229], v[82:85]
	v_mfma_f32_16x16x32_bf16 v[74:77], v[178:181], v[226:229], v[74:77]
	v_mfma_f32_16x16x32_bf16 v[70:73], v[170:173], v[240:243], v[70:73]
	v_mfma_f32_16x16x32_bf16 v[66:69], v[178:181], v[240:243], v[66:69]
	s_setprio 0
	s_barrier
; #define PG8_STAGE(bufoff, gbase, voff) do { _Pragma("unroll") for (int _i = 0; _i < 2; ++_i) \
;         __builtin_amdgcn_global_load_lds((const unsigned*)((const char*)(gbase) + (voff)[_i]), (PG8_LAS unsigned*)(lds + (bufoff) + ldsw + _i * 8192), 16, 0, 0); } while (0)
; #define PG8_LDA(dst, b, h) do { _Pragma("unroll") for (int m = 0; m < 4; ++m) _Pragma("unroll") for (int k = 0; k < 2; ++k) dst[m][k] = *(const PG8_LAS bf16x8*)(lds + PG8_SA(b, h) + aoff + m * 2048 + k * 1024); } while (0)
; #define PG8_MMA(ai, bj, At, Bt) do { __builtin_amdgcn_s_setprio(1); _Pragma("unroll") for (int m = 0; m < 4; ++m) _Pragma("unroll") for (int n = 0; n < 2; ++n) _Pragma("unroll") for (int k = 0; k < 2; ++k) \
;         acc[ai][bj][m][n] = __builtin_amdgcn_mfma_f32_16x16x32_bf16(Bt[n][k], At[m][k], acc[ai][bj][m][n], 0, 0, 0); __builtin_amdgcn_s_setprio(0); } while (0)
; #define PG8_WAIT_V(n) asm volatile("s_waitcnt vmcnt(" #n ")" ::: "memory")
; #define PG8_WAIT_L(n) asm volatile("s_waitcnt lgkmcnt(" #n ")" ::: "memory")
; #define PG8_BAR __builtin_amdgcn_s_barrier()
; #define PG8_SCHED __builtin_amdgcn_sched_barrier(0)
; template <class Epi, class Sched, bool ALIGN_EPI = false, bool SP2 = false>
; __device__ __forceinline__ void gemm_phase(PG8_LAS unsigned char* lds, const Gemm g, const Sched& S, const Epi& E) {
;     ...
;             PG8_LDA(At, 1, 1); PG8_STAGE(PG8_SB(1, 0), b3, voffB); PG8_STAGE(PG8_SB(1, 1), b3 + hstep, voffB); PG8_STAGE(PG8_SA(1, 0), a3, voffA);
;             PG8_WAIT_V(8); PG8_WAIT_L(0); PG8_BAR; PG8_MMA(1, 0, At, B0); PG8_MMA(1, 1, At, B1); PG8_BAR; PG8_SCHED;
	s_add_i32 s18, s36, s20
	v_lshl_add_u64 v[204:205], v[234:235], 0, s[42:43]
	s_mov_b32 m0, s18
	ds_read_b128 v[182:185], v147 offset:49152
	ds_read_b128 v[186:189], v147 offset:50176
	ds_read_b128 v[190:193], v147 offset:51200
	ds_read_b128 v[194:197], v147 offset:52224
	ds_read_b128 v[222:225], v147 offset:53248
	ds_read_b128 v[226:229], v147 offset:54272
	ds_read_b128 v[230:233], v147 offset:55296
	ds_read_b128 v[240:243], v147 offset:56320
	global_load_lds_dwordx4 v[204:205], off
	s_add_i32 m0, s18, 0x2000
	s_add_u32 s2, s2, 0x80080
	v_lshl_add_u64 v[204:205], v[244:245], 0, s[42:43]
	s_addc_u32 s3, s3, 0
	s_add_i32 s18, s37, s20
	global_load_lds_dwordx4 v[204:205], off
	v_lshl_add_u64 v[204:205], s[2:3], 0, v[0:1]
	s_mov_b32 m0, s18
	s_nop 0
	global_load_lds_dwordx4 v[204:205], off
	v_lshl_add_u64 v[204:205], s[2:3], 0, v[130:131]
	s_add_i32 m0, s18, 0x2000
	s_nop 0
	global_load_lds_dwordx4 v[204:205], off
	v_lshl_add_u64 v[204:205], v[246:247], 0, s[42:43]
	s_mov_b32 m0, s25
	s_nop 0
	global_load_lds_dwordx4 v[204:205], off
	v_lshl_add_u64 v[204:205], v[248:249], 0, s[42:43]
	s_mov_b32 m0, s26
	s_nop 0
	global_load_lds_dwordx4 v[204:205], off
	s_waitcnt vmcnt(8)
	s_waitcnt lgkmcnt(0)
	s_barrier
	s_setprio 1
	s_waitcnt lgkmcnt(0)
	v_mfma_f32_16x16x32_bf16 v[62:65], v[140:143], v[182:185], v[62:65]
	v_mfma_f32_16x16x32_bf16 v[58:61], v[152:155], v[182:185], v[58:61]
	v_mfma_f32_16x16x32_bf16 v[54:57], v[140:143], v[190:193], v[54:57]
	v_mfma_f32_16x16x32_bf16 v[46:49], v[152:155], v[190:193], v[46:49]
	v_mfma_f32_16x16x32_bf16 v[38:41], v[140:143], v[222:225], v[38:41]
	v_mfma_f32_16x16x32_bf16 v[30:33], v[152:155], v[222:225], v[30:33]
	v_mfma_f32_16x16x32_bf16 v[22:25], v[140:143], v[230:233], v[22:25]
	v_mfma_f32_16x16x32_bf16 v[14:17], v[152:155], v[230:233], v[14:17]
	v_mfma_f32_16x16x32_bf16 v[62:65], v[148:151], v[186:189], v[62:65]
	v_mfma_f32_16x16x32_bf16 v[58:61], v[156:159], v[186:189], v[58:61]
	v_mfma_f32_16x16x32_bf16 v[54:57], v[148:151], v[194:197], v[54:57]
	v_mfma_f32_16x16x32_bf16 v[46:49], v[156:159], v[194:197], v[46:49]
	v_mfma_f32_16x16x32_bf16 v[38:41], v[148:151], v[226:229], v[38:41]
	v_mfma_f32_16x16x32_bf16 v[30:33], v[156:159], v[226:229], v[30:33]
	v_mfma_f32_16x16x32_bf16 v[22:25], v[148:151], v[240:243], v[22:25]
	v_mfma_f32_16x16x32_bf16 v[14:17], v[156:159], v[240:243], v[14:17]
	s_setprio 0
	s_setprio 1
	v_mfma_f32_16x16x32_bf16 v[50:53], v[160:163], v[182:185], v[50:53]
	v_mfma_f32_16x16x32_bf16 v[42:45], v[174:177], v[182:185], v[42:45]
	v_mfma_f32_16x16x32_bf16 v[34:37], v[160:163], v[190:193], v[34:37]
	v_mfma_f32_16x16x32_bf16 v[26:29], v[174:177], v[190:193], v[26:29]
	v_mfma_f32_16x16x32_bf16 v[18:21], v[160:163], v[222:225], v[18:21]
	v_mfma_f32_16x16x32_bf16 v[10:13], v[174:177], v[222:225], v[10:13]
	v_mfma_f32_16x16x32_bf16 v[6:9], v[160:163], v[230:233], v[6:9]
	v_mfma_f32_16x16x32_bf16 v[2:5], v[174:177], v[230:233], v[2:5]
	v_mfma_f32_16x16x32_bf16 v[50:53], v[170:173], v[186:189], v[50:53]
	v_mfma_f32_16x16x32_bf16 v[42:45], v[178:181], v[186:189], v[42:45]
	v_mfma_f32_16x16x32_bf16 v[34:37], v[170:173], v[194:197], v[34:37]
	v_mfma_f32_16x16x32_bf16 v[26:29], v[178:181], v[194:197], v[26:29]
	v_mfma_f32_16x16x32_bf16 v[18:21], v[170:173], v[226:229], v[18:21]
	v_mfma_f32_16x16x32_bf16 v[10:13], v[178:181], v[226:229], v[10:13]
	v_mfma_f32_16x16x32_bf16 v[6:9], v[170:173], v[240:243], v[6:9]
	v_mfma_f32_16x16x32_bf16 v[2:5], v[178:181], v[240:243], v[2:5]
	s_setprio 0
	s_add_i32 s35, s35, 2
	s_add_u32 s16, s16, 0x100
	s_addc_u32 s17, s17, 0
	s_add_u32 s33, s33, 0x100
	s_addc_u32 s34, s34, 0
	s_cmp_gt_u32 s35, 29
	s_barrier
	s_cbranch_scc0 .LBB0_323
	s_and_b64 vcc, exec, s[6:7]
	v_readlane_b32 s33, v254, 33
	s_cbranch_vccz .LBB0_326
	s_barrier

;     __host__ __device__ bool next(int i, Unit& u) const { if (!base.next(i >> 2, u)) return false; u.z = i & 3; return true; }
;     __host__ __device__ bool next(int i, Unit& u) const { const int L = i * G + c; if (L >= nunits) return false; const int t = L >> 2; u.z = L & 3; u.pm = t / nN; u.pn = t % nN; return true; }
; #define PG8_STAGE(bufoff, gbase, voff) do { _Pragma("unroll") for (int _i = 0; _i < 2; ++_i) \
;         __builtin_amdgcn_global_load_lds((const unsigned*)((const char*)(gbase) + (voff)[_i]), (PG8_LAS unsigned*)(lds + (bufoff) + ldsw + _i * 8192), 16, 0, 0); } while (0)
; #define PG8_LDA(dst, b, h) do { _Pragma("unroll") for (int m = 0; m < 4; ++m) _Pragma("unroll") for (int k = 0; k < 2; ++k) dst[m][k] = *(const PG8_LAS bf16x8*)(lds + PG8_SA(b, h) + aoff + m * 2048 + k * 1024); } while (0)
; #define PG8_WAIT_V(n) asm volatile("s_waitcnt vmcnt(" #n ")" ::: "memory")
; #define PG8_WAIT_L(n) asm volatile("s_waitcnt lgkmcnt(" #n ")" ::: "memory")
; template <class Epi, class Sched, bool ALIGN_EPI = false, bool SP2 = false>
; __device__ __forceinline__ void gemm_phase(PG8_LAS unsigned char* lds, const Gemm g, const Sched& S, const Epi& E) {
;     ...
;         const bool has_next = S.next(ui + 1, nxt);
;         const char* nA = has_next ? (const char*)g.A + (size_t)nxt.pm * tstep + (size_t)nxt.z * g.zA : cA; const char* nB = has_next ? (const char*)g.Bt + (size_t)nxt.pn * tstep + (size_t)nxt.z * g.zB : cB;
;         for (int t = 0; t < nt; t += 2) {
;             const bool last = (t == nt - 2);
;             const char* a1 = cA + (size_t)(t + 1) * kstep;
;             const char* a2 = last ? nA : cA + (size_t)(t + 2) * kstep; const char* b2 = last ? nB : cB + (size_t)(t + 2) * kstep;
;             const char* a3 = a2 + kstep; const char* b3 = b2 + kstep;
;             if (last && has_next) S.a_ready(nxt);
;             if constexpr (SP2) {
;             PG8_LDB(B0, 0, 0); PG8_LDB(B1, 0, 1); PG8_SCHED; PG8_LDA(At, 0, 0); PG8_STAGE(PG8_SA(1, 1), a1 + hstep, voffA);
;             PG8_WAIT_V(8); PG8_WAIT_L(0); PG8_BAR; PG8_MMA(0, 0, At, B0); PG8_MMA(0, 1, At, B1); PG8_BAR; PG8_SCHED;
;             PG8_LDA(At, 0, 1); PG8_STAGE(PG8_SB(0, 0), b2, voffB); PG8_STAGE(PG8_SB(0, 1), b2 + hstep, voffB); PG8_STAGE(PG8_SA(0, 0), a2, voffA);
;             PG8_WAIT_V(8); PG8_WAIT_L(0); PG8_BAR; PG8_MMA(1, 0, At, B0); PG8_MMA(1, 1, At, B1); PG8_BAR; PG8_SCHED;
.LBB0_1153:
	s_add_u32 s2, s0, 0xfffe0080
	s_addc_u32 s3, s1, -1
	s_add_i32 s23, 0, 0x10000
	s_cmp_eq_u32 s21, 4
	s_cselect_b32 s9, s25, s3
	s_cselect_b32 s8, s24, s2
	v_add_u32_e32 v0, s23, v197
	s_cselect_b32 s3, s7, s19
	s_cselect_b32 s2, s10, s11
	s_add_i32 s39, 0, 0x14000
	ds_read_b128 v[132:135], v0
	ds_read_b128 v[136:139], v0 offset:1024
	ds_read_b128 v[140:143], v0 offset:2048
	ds_read_b128 v[144:147], v0 offset:3072
	v_add_u32_e32 v0, s39, v197
	ds_read_b128 v[148:151], v0
	ds_read_b128 v[152:155], v0 offset:1024
	ds_read_b128 v[156:159], v0 offset:2048
	ds_read_b128 v[160:163], v0 offset:3072
	v_lshl_add_u64 v[2:3], s[0:1], 0, v[178:179]
	s_add_i32 m0, s29, 0xc000
	ds_read_b128 v[182:185], v223
	ds_read_b128 v[186:189], v223 offset:1024
	ds_read_b128 v[190:193], v223 offset:2048
	ds_read_b128 v[224:227], v223 offset:3072
	ds_read_b128 v[228:231], v223 offset:4096
	ds_read_b128 v[232:235], v223 offset:5120
	ds_read_b128 v[240:243], v223 offset:6144
	ds_read_b128 v[244:247], v223 offset:7168
	global_load_lds_dwordx4 v[2:3], off
	v_lshl_add_u64 v[2:3], s[0:1], 0, v[180:181]
	s_add_i32 m0, s29, 0xe000
	s_nop 0
	global_load_lds_dwordx4 v[2:3], off
	s_waitcnt vmcnt(8)
	s_waitcnt lgkmcnt(0)
	s_barrier
	s_setprio 1
	s_waitcnt lgkmcnt(0)
	v_mfma_f32_16x16x32_bf16 v[128:131], v[132:135], v[182:185], v[128:131]
	v_mfma_f32_16x16x32_bf16 v[124:127], v[140:143], v[182:185], v[124:127]
	v_mfma_f32_16x16x32_bf16 v[120:123], v[132:135], v[190:193], v[120:123]
	v_mfma_f32_16x16x32_bf16 v[116:119], v[140:143], v[190:193], v[116:119]
	v_mfma_f32_16x16x32_bf16 v[112:115], v[132:135], v[228:231], v[112:115]
	v_mfma_f32_16x16x32_bf16 v[108:111], v[140:143], v[228:231], v[108:111]
	v_mfma_f32_16x16x32_bf16 v[104:107], v[132:135], v[240:243], v[104:107]
	v_mfma_f32_16x16x32_bf16 v[100:103], v[140:143], v[240:243], v[100:103]
	v_mfma_f32_16x16x32_bf16 v[128:131], v[136:139], v[186:189], v[128:131]
	v_mfma_f32_16x16x32_bf16 v[124:127], v[144:147], v[186:189], v[124:127]
	v_mfma_f32_16x16x32_bf16 v[120:123], v[136:139], v[224:227], v[120:123]
	v_mfma_f32_16x16x32_bf16 v[116:119], v[144:147], v[224:227], v[116:119]
	v_mfma_f32_16x16x32_bf16 v[112:115], v[136:139], v[232:235], v[112:115]
	v_mfma_f32_16x16x32_bf16 v[108:111], v[144:147], v[232:235], v[108:111]
	v_mfma_f32_16x16x32_bf16 v[104:107], v[136:139], v[244:247], v[104:107]
	v_mfma_f32_16x16x32_bf16 v[100:103], v[144:147], v[244:247], v[100:103]
	s_setprio 0
	s_setprio 1
	v_mfma_f32_16x16x32_bf16 v[96:99], v[148:151], v[182:185], v[96:99]
	v_mfma_f32_16x16x32_bf16 v[92:95], v[156:159], v[182:185], v[92:95]
	v_mfma_f32_16x16x32_bf16 v[88:91], v[148:151], v[190:193], v[88:91]
	v_mfma_f32_16x16x32_bf16 v[84:87], v[156:159], v[190:193], v[84:87]
	v_mfma_f32_16x16x32_bf16 v[80:83], v[148:151], v[228:231], v[80:83]
	v_mfma_f32_16x16x32_bf16 v[76:79], v[156:159], v[228:231], v[76:79]
	v_mfma_f32_16x16x32_bf16 v[72:75], v[148:151], v[240:243], v[72:75]
	v_mfma_f32_16x16x32_bf16 v[68:71], v[156:159], v[240:243], v[68:71]
	v_mfma_f32_16x16x32_bf16 v[96:99], v[152:155], v[186:189], v[96:99]
	v_mfma_f32_16x16x32_bf16 v[92:95], v[160:163], v[186:189], v[92:95]
	v_mfma_f32_16x16x32_bf16 v[88:91], v[152:155], v[224:227], v[88:91]
	v_mfma_f32_16x16x32_bf16 v[84:87], v[160:163], v[224:227], v[84:87]
	v_mfma_f32_16x16x32_bf16 v[80:83], v[152:155], v[232:235], v[80:83]
	v_mfma_f32_16x16x32_bf16 v[76:79], v[160:163], v[232:235], v[76:79]
	v_mfma_f32_16x16x32_bf16 v[72:75], v[152:155], v[244:247], v[72:75]
	v_mfma_f32_16x16x32_bf16 v[68:71], v[160:163], v[244:247], v[68:71]
	s_setprio 0
	s_barrier
	s_add_i32 s23, s23, s28
	v_lshl_add_u64 v[194:195], s[2:3], 0, v[172:173]
	s_mov_b32 m0, s23
	ds_read_b128 v[182:185], v223 offset:16384
	ds_read_b128 v[186:189], v223 offset:17408
	ds_read_b128 v[190:193], v223 offset:18432
	ds_read_b128 v[224:227], v223 offset:19456
	ds_read_b128 v[228:231], v223 offset:20480
	ds_read_b128 v[232:235], v223 offset:21504
	ds_read_b128 v[240:243], v223 offset:22528
	ds_read_b128 v[244:247], v223 offset:23552
	global_load_lds_dwordx4 v[194:195], off
	s_add_i32 m0, s23, 0x2000
	s_add_u32 s42, s2, 0x20000
	v_lshl_add_u64 v[204:205], s[2:3], 0, v[176:177]
	s_addc_u32 s43, s3, 0
	s_add_i32 s23, s39, s28
	global_load_lds_dwordx4 v[204:205], off
	v_lshl_add_u64 v[2:3], s[42:43], 0, v[172:173]
	s_mov_b32 m0, s23
	v_lshl_add_u64 v[248:249], s[8:9], 0, v[170:171]
	global_load_lds_dwordx4 v[2:3], off
	v_lshl_add_u64 v[2:3], s[42:43], 0, v[176:177]
	s_add_i32 m0, s23, 0x2000
	v_lshl_add_u64 v[214:215], s[8:9], 0, v[174:175]
	global_load_lds_dwordx4 v[2:3], off
	s_mov_b32 m0, s29
	s_nop 0
	global_load_lds_dwordx4 v[248:249], off
	s_mov_b32 m0, s30
	s_nop 0
	global_load_lds_dwordx4 v[214:215], off
	s_waitcnt vmcnt(8)
	s_waitcnt lgkmcnt(0)
	s_barrier
; #define PG8_STAGE(bufoff, gbase, voff) do { _Pragma("unroll") for (int _i = 0; _i < 2; ++_i) \
;         __builtin_amdgcn_global_load_lds((const unsigned*)((const char*)(gbase) + (voff)[_i]), (PG8_LAS unsigned*)(lds + (bufoff) + ldsw + _i * 8192), 16, 0, 0); } while (0)
; #define PG8_LDA(dst, b, h) do { _Pragma("unroll") for (int m = 0; m < 4; ++m) _Pragma("unroll") for (int k = 0; k < 2; ++k) dst[m][k] = *(const PG8_LAS bf16x8*)(lds + PG8_SA(b, h) + aoff + m * 2048 + k * 1024); } while (0)
; #define PG8_LDB(dst, b, h) do { _Pragma("unroll") for (int n = 0; n < 2; ++n) _Pragma("unroll") for (int k = 0; k < 2; ++k) dst[n][k] = *(const PG8_LAS bf16x8*)(lds + PG8_SB(b, h) + boff + n * 2048 + k * 1024); } while (0)
; #define PG8_MMA(ai, bj, At, Bt) do { __builtin_amdgcn_s_setprio(1); _Pragma("unroll") for (int m = 0; m < 4; ++m) _Pragma("unroll") for (int n = 0; n < 2; ++n) _Pragma("unroll") for (int k = 0; k < 2; ++k) \
;         acc[ai][bj][m][n] = __builtin_amdgcn_mfma_f32_16x16x32_bf16(Bt[n][k], At[m][k], acc[ai][bj][m][n], 0, 0, 0); __builtin_amdgcn_s_setprio(0); } while (0)
; #define PG8_WAIT_V(n) asm volatile("s_waitcnt vmcnt(" #n ")" ::: "memory")
; #define PG8_WAIT_L(n) asm volatile("s_waitcnt lgkmcnt(" #n ")" ::: "memory")
; #define PG8_BAR __builtin_amdgcn_s_barrier()
; #define PG8_SCHED __builtin_amdgcn_sched_barrier(0)
; template <class Epi, class Sched, bool ALIGN_EPI = false, bool SP2 = false>
; __device__ __forceinline__ void gemm_phase(PG8_LAS unsigned char* lds, const Gemm g, const Sched& S, const Epi& E) {
;     ...
;             PG8_WAIT_V(8); PG8_WAIT_L(0); PG8_BAR; PG8_MMA(1, 0, At, B0); PG8_MMA(1, 1, At, B1); PG8_BAR; PG8_SCHED;
;             PG8_LDB(B0, 1, 0); PG8_LDB(B1, 1, 1); PG8_SCHED; PG8_LDA(At, 1, 0); PG8_STAGE(PG8_SA(0, 1), a2 + hstep, voffA);
;             PG8_WAIT_V(8); PG8_WAIT_L(0); PG8_BAR; PG8_MMA(0, 0, At, B0); PG8_MMA(0, 1, At, B1); PG8_BAR; PG8_SCHED;
	s_setprio 1
	s_waitcnt lgkmcnt(0)
	v_mfma_f32_16x16x32_bf16 v[64:67], v[132:135], v[182:185], v[64:67]
	v_mfma_f32_16x16x32_bf16 v[60:63], v[140:143], v[182:185], v[60:63]
	v_mfma_f32_16x16x32_bf16 v[56:59], v[132:135], v[190:193], v[56:59]
	v_mfma_f32_16x16x32_bf16 v[52:55], v[140:143], v[190:193], v[52:55]
	v_mfma_f32_16x16x32_bf16 v[48:51], v[132:135], v[228:231], v[48:51]
	v_mfma_f32_16x16x32_bf16 v[44:47], v[140:143], v[228:231], v[44:47]
	v_mfma_f32_16x16x32_bf16 v[40:43], v[132:135], v[240:243], v[40:43]
	v_mfma_f32_16x16x32_bf16 v[36:39], v[140:143], v[240:243], v[36:39]
	v_mfma_f32_16x16x32_bf16 v[64:67], v[136:139], v[186:189], v[64:67]
	v_mfma_f32_16x16x32_bf16 v[60:63], v[144:147], v[186:189], v[60:63]
	v_mfma_f32_16x16x32_bf16 v[56:59], v[136:139], v[224:227], v[56:59]
	v_mfma_f32_16x16x32_bf16 v[52:55], v[144:147], v[224:227], v[52:55]
	v_mfma_f32_16x16x32_bf16 v[48:51], v[136:139], v[232:235], v[48:51]
	v_mfma_f32_16x16x32_bf16 v[44:47], v[144:147], v[232:235], v[44:47]
	v_mfma_f32_16x16x32_bf16 v[40:43], v[136:139], v[244:247], v[40:43]
	v_mfma_f32_16x16x32_bf16 v[36:39], v[144:147], v[244:247], v[36:39]
	s_setprio 0
	s_setprio 1
	v_mfma_f32_16x16x32_bf16 v[32:35], v[148:151], v[182:185], v[32:35]
	v_mfma_f32_16x16x32_bf16 v[28:31], v[156:159], v[182:185], v[28:31]
	v_mfma_f32_16x16x32_bf16 v[24:27], v[148:151], v[190:193], v[24:27]
	v_mfma_f32_16x16x32_bf16 v[20:23], v[156:159], v[190:193], v[20:23]
	v_mfma_f32_16x16x32_bf16 v[16:19], v[148:151], v[228:231], v[16:19]
	v_mfma_f32_16x16x32_bf16 v[12:15], v[156:159], v[228:231], v[12:15]
	v_mfma_f32_16x16x32_bf16 v[8:11], v[148:151], v[240:243], v[8:11]
	v_mfma_f32_16x16x32_bf16 v[2:5], v[156:159], v[240:243], v[4:7]
	v_mfma_f32_16x16x32_bf16 v[32:35], v[152:155], v[186:189], v[32:35]
	v_mfma_f32_16x16x32_bf16 v[28:31], v[160:163], v[186:189], v[28:31]
	v_mfma_f32_16x16x32_bf16 v[24:27], v[152:155], v[224:227], v[24:27]
	v_mfma_f32_16x16x32_bf16 v[20:23], v[160:163], v[224:227], v[20:23]
	v_mfma_f32_16x16x32_bf16 v[16:19], v[152:155], v[232:235], v[16:19]
	v_mfma_f32_16x16x32_bf16 v[12:15], v[160:163], v[232:235], v[12:15]
	v_mfma_f32_16x16x32_bf16 v[8:11], v[152:155], v[244:247], v[8:11]
	v_mfma_f32_16x16x32_bf16 v[2:5], v[160:163], v[244:247], v[2:5]
	s_setprio 0
	s_barrier
	s_add_i32 s23, 0, 0x18000
	v_add_u32_e32 v0, s23, v197
	s_add_i32 s39, 0, 0x1c000
	ds_read_b128 v[132:135], v0
	ds_read_b128 v[136:139], v0 offset:1024
	ds_read_b128 v[140:143], v0 offset:2048
	ds_read_b128 v[144:147], v0 offset:3072
	v_add_u32_e32 v0, s39, v197
	ds_read_b128 v[148:151], v0
	ds_read_b128 v[152:155], v0 offset:1024
	ds_read_b128 v[156:159], v0 offset:2048
	ds_read_b128 v[160:163], v0 offset:3072
	s_add_u32 s8, s8, 0x20000
	s_addc_u32 s9, s9, 0
	s_mov_b32 m0, s31
	v_lshl_add_u64 v[6:7], s[8:9], 0, v[170:171]
	ds_read_b128 v[182:185], v223 offset:32768
	ds_read_b128 v[186:189], v223 offset:33792
	ds_read_b128 v[190:193], v223 offset:34816
	ds_read_b128 v[224:227], v223 offset:35840
	ds_read_b128 v[228:231], v223 offset:36864
	ds_read_b128 v[232:235], v223 offset:37888
	ds_read_b128 v[240:243], v223 offset:38912
	ds_read_b128 v[244:247], v223 offset:39936
	global_load_lds_dwordx4 v[6:7], off
	v_lshl_add_u64 v[6:7], s[8:9], 0, v[174:175]
	s_mov_b32 m0, s33
	s_nop 0
	global_load_lds_dwordx4 v[6:7], off
	s_waitcnt vmcnt(8)
	s_waitcnt lgkmcnt(0)
	s_barrier
	s_setprio 1
	s_waitcnt lgkmcnt(0)
	v_mfma_f32_16x16x32_bf16 v[128:131], v[132:135], v[182:185], v[128:131]
	v_mfma_f32_16x16x32_bf16 v[124:127], v[140:143], v[182:185], v[124:127]
	v_mfma_f32_16x16x32_bf16 v[120:123], v[132:135], v[190:193], v[120:123]
	v_mfma_f32_16x16x32_bf16 v[116:119], v[140:143], v[190:193], v[116:119]
	v_mfma_f32_16x16x32_bf16 v[112:115], v[132:135], v[228:231], v[112:115]
	v_mfma_f32_16x16x32_bf16 v[108:111], v[140:143], v[228:231], v[108:111]
	v_mfma_f32_16x16x32_bf16 v[104:107], v[132:135], v[240:243], v[104:107]
	v_mfma_f32_16x16x32_bf16 v[100:103], v[140:143], v[240:243], v[100:103]
	v_mfma_f32_16x16x32_bf16 v[128:131], v[136:139], v[186:189], v[128:131]
	v_mfma_f32_16x16x32_bf16 v[124:127], v[144:147], v[186:189], v[124:127]
	v_mfma_f32_16x16x32_bf16 v[120:123], v[136:139], v[224:227], v[120:123]
	v_mfma_f32_16x16x32_bf16 v[116:119], v[144:147], v[224:227], v[116:119]
	v_mfma_f32_16x16x32_bf16 v[112:115], v[136:139], v[232:235], v[112:115]
	v_mfma_f32_16x16x32_bf16 v[108:111], v[144:147], v[232:235], v[108:111]
	v_mfma_f32_16x16x32_bf16 v[104:107], v[136:139], v[244:247], v[104:107]
	v_mfma_f32_16x16x32_bf16 v[100:103], v[144:147], v[244:247], v[100:103]
	s_setprio 0
	s_setprio 1
	v_mfma_f32_16x16x32_bf16 v[96:99], v[148:151], v[182:185], v[96:99]
	v_mfma_f32_16x16x32_bf16 v[92:95], v[156:159], v[182:185], v[92:95]
	v_mfma_f32_16x16x32_bf16 v[88:91], v[148:151], v[190:193], v[88:91]
	v_mfma_f32_16x16x32_bf16 v[84:87], v[156:159], v[190:193], v[84:87]
	v_mfma_f32_16x16x32_bf16 v[80:83], v[148:151], v[228:231], v[80:83]
	v_mfma_f32_16x16x32_bf16 v[76:79], v[156:159], v[228:231], v[76:79]
	v_mfma_f32_16x16x32_bf16 v[72:75], v[148:151], v[240:243], v[72:75]
	v_mfma_f32_16x16x32_bf16 v[68:71], v[156:159], v[240:243], v[68:71]
	v_mfma_f32_16x16x32_bf16 v[96:99], v[152:155], v[186:189], v[96:99]
	v_mfma_f32_16x16x32_bf16 v[92:95], v[160:163], v[186:189], v[92:95]
	v_mfma_f32_16x16x32_bf16 v[88:91], v[152:155], v[224:227], v[88:91]
	v_mfma_f32_16x16x32_bf16 v[84:87], v[160:163], v[224:227], v[84:87]
	v_mfma_f32_16x16x32_bf16 v[80:83], v[152:155], v[232:235], v[80:83]
	v_mfma_f32_16x16x32_bf16 v[76:79], v[160:163], v[232:235], v[76:79]
	v_mfma_f32_16x16x32_bf16 v[72:75], v[152:155], v[244:247], v[72:75]
	v_mfma_f32_16x16x32_bf16 v[68:71], v[160:163], v[244:247], v[68:71]
	s_setprio 0
	s_barrier
; #define PG8_STAGE(bufoff, gbase, voff) do { _Pragma("unroll") for (int _i = 0; _i < 2; ++_i) \
;         __builtin_amdgcn_global_load_lds((const unsigned*)((const char*)(gbase) + (voff)[_i]), (PG8_LAS unsigned*)(lds + (bufoff) + ldsw + _i * 8192), 16, 0, 0); } while (0)
; #define PG8_LDA(dst, b, h) do { _Pragma("unroll") for (int m = 0; m < 4; ++m) _Pragma("unroll") for (int k = 0; k < 2; ++k) dst[m][k] = *(const PG8_LAS bf16x8*)(lds + PG8_SA(b, h) + aoff + m * 2048 + k * 1024); } while (0)
; #define PG8_MMA(ai, bj, At, Bt) do { __builtin_amdgcn_s_setprio(1); _Pragma("unroll") for (int m = 0; m < 4; ++m) _Pragma("unroll") for (int n = 0; n < 2; ++n) _Pragma("unroll") for (int k = 0; k < 2; ++k) \
;         acc[ai][bj][m][n] = __builtin_amdgcn_mfma_f32_16x16x32_bf16(Bt[n][k], At[m][k], acc[ai][bj][m][n], 0, 0, 0); __builtin_amdgcn_s_setprio(0); } while (0)
; #define PG8_WAIT_V(n) asm volatile("s_waitcnt vmcnt(" #n ")" ::: "memory")
; #define PG8_WAIT_L(n) asm volatile("s_waitcnt lgkmcnt(" #n ")" ::: "memory")
; #define PG8_BAR __builtin_amdgcn_s_barrier()
; #define PG8_SCHED __builtin_amdgcn_sched_barrier(0)
; template <class Epi, class Sched, bool ALIGN_EPI = false, bool SP2 = false>
; __device__ __forceinline__ void gemm_phase(PG8_LAS unsigned char* lds, const Gemm g, const Sched& S, const Epi& E) {
;     ...
;             PG8_LDA(At, 1, 1); PG8_STAGE(PG8_SB(1, 0), b3, voffB); PG8_STAGE(PG8_SB(1, 1), b3 + hstep, voffB); PG8_STAGE(PG8_SA(1, 0), a3, voffA);
;             PG8_WAIT_V(8); PG8_WAIT_L(0); PG8_BAR; PG8_MMA(1, 0, At, B0); PG8_MMA(1, 1, At, B1); PG8_BAR; PG8_SCHED;
	s_add_i32 s8, s23, s28
	v_lshl_add_u64 v[6:7], v[194:195], 0, s[46:47]
	s_mov_b32 m0, s8
	ds_read_b128 v[182:185], v223 offset:49152
	ds_read_b128 v[186:189], v223 offset:50176
	ds_read_b128 v[190:193], v223 offset:51200
	ds_read_b128 v[224:227], v223 offset:52224
	ds_read_b128 v[228:231], v223 offset:53248
	ds_read_b128 v[232:235], v223 offset:54272
	ds_read_b128 v[240:243], v223 offset:55296
	ds_read_b128 v[244:247], v223 offset:56320
	global_load_lds_dwordx4 v[6:7], off
	s_add_i32 m0, s8, 0x2000
	s_add_u32 s2, s2, 0x20080
	v_lshl_add_u64 v[6:7], v[204:205], 0, s[46:47]
	s_addc_u32 s3, s3, 0
	s_add_i32 s8, s39, s28
	global_load_lds_dwordx4 v[6:7], off
	v_lshl_add_u64 v[6:7], s[2:3], 0, v[172:173]
	s_mov_b32 m0, s8
	s_nop 0
	global_load_lds_dwordx4 v[6:7], off
	v_lshl_add_u64 v[6:7], s[2:3], 0, v[176:177]
	s_add_i32 m0, s8, 0x2000
	s_nop 0
	global_load_lds_dwordx4 v[6:7], off
	v_lshl_add_u64 v[6:7], v[248:249], 0, s[46:47]
	s_mov_b32 m0, s36
	s_nop 0
	global_load_lds_dwordx4 v[6:7], off
	v_lshl_add_u64 v[6:7], v[214:215], 0, s[46:47]
	s_mov_b32 m0, s37
	s_nop 0
	global_load_lds_dwordx4 v[6:7], off
	s_waitcnt vmcnt(8)
	s_waitcnt lgkmcnt(0)
	s_barrier
	s_setprio 1
	s_waitcnt lgkmcnt(0)
	v_mfma_f32_16x16x32_bf16 v[64:67], v[132:135], v[182:185], v[64:67]
	v_mfma_f32_16x16x32_bf16 v[60:63], v[140:143], v[182:185], v[60:63]
	v_mfma_f32_16x16x32_bf16 v[56:59], v[132:135], v[190:193], v[56:59]
	v_mfma_f32_16x16x32_bf16 v[52:55], v[140:143], v[190:193], v[52:55]
	v_mfma_f32_16x16x32_bf16 v[48:51], v[132:135], v[228:231], v[48:51]
	v_mfma_f32_16x16x32_bf16 v[44:47], v[140:143], v[228:231], v[44:47]
	v_mfma_f32_16x16x32_bf16 v[40:43], v[132:135], v[240:243], v[40:43]
	v_mfma_f32_16x16x32_bf16 v[36:39], v[140:143], v[240:243], v[36:39]
	v_mfma_f32_16x16x32_bf16 v[64:67], v[136:139], v[186:189], v[64:67]
	v_mfma_f32_16x16x32_bf16 v[60:63], v[144:147], v[186:189], v[60:63]
	v_mfma_f32_16x16x32_bf16 v[56:59], v[136:139], v[224:227], v[56:59]
	v_mfma_f32_16x16x32_bf16 v[52:55], v[144:147], v[224:227], v[52:55]
	v_mfma_f32_16x16x32_bf16 v[48:51], v[136:139], v[232:235], v[48:51]
	v_mfma_f32_16x16x32_bf16 v[44:47], v[144:147], v[232:235], v[44:47]
	v_mfma_f32_16x16x32_bf16 v[40:43], v[136:139], v[244:247], v[40:43]
	v_mfma_f32_16x16x32_bf16 v[36:39], v[144:147], v[244:247], v[36:39]
	s_setprio 0
	s_setprio 1
	v_mfma_f32_16x16x32_bf16 v[32:35], v[148:151], v[182:185], v[32:35]
	v_mfma_f32_16x16x32_bf16 v[28:31], v[156:159], v[182:185], v[28:31]
	v_mfma_f32_16x16x32_bf16 v[24:27], v[148:151], v[190:193], v[24:27]
	v_mfma_f32_16x16x32_bf16 v[20:23], v[156:159], v[190:193], v[20:23]
	v_mfma_f32_16x16x32_bf16 v[16:19], v[148:151], v[228:231], v[16:19]
	v_mfma_f32_16x16x32_bf16 v[12:15], v[156:159], v[228:231], v[12:15]
	v_mfma_f32_16x16x32_bf16 v[6:9], v[148:151], v[240:243], v[8:11]
	v_mfma_f32_16x16x32_bf16 v[2:5], v[156:159], v[240:243], v[2:5]
	v_mfma_f32_16x16x32_bf16 v[32:35], v[152:155], v[186:189], v[32:35]
	v_mfma_f32_16x16x32_bf16 v[28:31], v[160:163], v[186:189], v[28:31]
	v_mfma_f32_16x16x32_bf16 v[24:27], v[152:155], v[224:227], v[24:27]
	v_mfma_f32_16x16x32_bf16 v[20:23], v[160:163], v[224:227], v[20:23]
	v_mfma_f32_16x16x32_bf16 v[16:19], v[152:155], v[232:235], v[16:19]
	v_mfma_f32_16x16x32_bf16 v[12:15], v[160:163], v[232:235], v[12:15]
	v_mfma_f32_16x16x32_bf16 v[8:11], v[152:155], v[244:247], v[6:9]
	v_mfma_f32_16x16x32_bf16 v[4:7], v[160:163], v[244:247], v[2:5]
	s_setprio 0
	s_add_i32 s21, s21, 2
	s_add_u32 s0, s0, 0x100
	s_addc_u32 s1, s1, 0
	s_add_u32 s11, s11, 0x100
	s_addc_u32 s19, s19, 0
	s_cmp_gt_u32 s21, 5
	s_barrier
	s_cbranch_scc0 .LBB0_1153
	s_and_b64 vcc, exec, s[16:17]
	s_cbranch_vccz .LBB0_1156
	s_barrier

;     __host__ __device__ bool next(int i, Unit& u) const { if (!base.next(i >> 2, u)) return false; u.z = i & 3; return true; }
;     __host__ __device__ bool next(int i, Unit& u) const { const int L = i * G + c; if (L >= nunits) return false; const int t = L >> 2; u.z = L & 3; u.pm = t / nN; u.pn = t % nN; return true; }
; #define PG8_STAGE(bufoff, gbase, voff) do { _Pragma("unroll") for (int _i = 0; _i < 2; ++_i) \
;         __builtin_amdgcn_global_load_lds((const unsigned*)((const char*)(gbase) + (voff)[_i]), (PG8_LAS unsigned*)(lds + (bufoff) + ldsw + _i * 8192), 16, 0, 0); } while (0)
; #define PG8_LDA(dst, b, h) do { _Pragma("unroll") for (int m = 0; m < 4; ++m) _Pragma("unroll") for (int k = 0; k < 2; ++k) dst[m][k] = *(const PG8_LAS bf16x8*)(lds + PG8_SA(b, h) + aoff + m * 2048 + k * 1024); } while (0)
; #define PG8_WAIT_V(n) asm volatile("s_waitcnt vmcnt(" #n ")" ::: "memory")
; #define PG8_WAIT_L(n) asm volatile("s_waitcnt lgkmcnt(" #n ")" ::: "memory")
; template <class Epi, class Sched, bool ALIGN_EPI = false, bool SP2 = false>
; __device__ __forceinline__ void gemm_phase(PG8_LAS unsigned char* lds, const Gemm g, const Sched& S, const Epi& E) {
;     ...
;         const bool has_next = S.next(ui + 1, nxt);
;         const char* nA = has_next ? (const char*)g.A + (size_t)nxt.pm * tstep + (size_t)nxt.z * g.zA : cA; const char* nB = has_next ? (const char*)g.Bt + (size_t)nxt.pn * tstep + (size_t)nxt.z * g.zB : cB;
;         for (int t = 0; t < nt; t += 2) {
;             const bool last = (t == nt - 2);
;             const char* a1 = cA + (size_t)(t + 1) * kstep;
;             const char* a2 = last ? nA : cA + (size_t)(t + 2) * kstep; const char* b2 = last ? nB : cB + (size_t)(t + 2) * kstep;
;             const char* a3 = a2 + kstep; const char* b3 = b2 + kstep;
;             if (last && has_next) S.a_ready(nxt);
;             if constexpr (SP2) {
;             PG8_LDB(B0, 0, 0); PG8_LDB(B1, 0, 1); PG8_SCHED; PG8_LDA(At, 0, 0); PG8_STAGE(PG8_SA(1, 1), a1 + hstep, voffA);
;             PG8_WAIT_V(8); PG8_WAIT_L(0); PG8_BAR; PG8_MMA(0, 0, At, B0); PG8_MMA(0, 1, At, B1); PG8_BAR; PG8_SCHED;
;             PG8_LDA(At, 0, 1); PG8_STAGE(PG8_SB(0, 0), b2, voffB); PG8_STAGE(PG8_SB(0, 1), b2 + hstep, voffB); PG8_STAGE(PG8_SA(0, 0), a2, voffA);
;             PG8_WAIT_V(8); PG8_WAIT_L(0); PG8_BAR; PG8_MMA(1, 0, At, B0); PG8_MMA(1, 1, At, B1); PG8_BAR; PG8_SCHED;
.LBB0_1346:
	s_add_u32 s2, s20, 0xfff80080
	s_addc_u32 s3, s21, -1
	s_add_i32 s37, 0, 0x10000
	s_cmp_eq_u32 s36, 28
	s_cselect_b32 s23, s11, s3
	s_cselect_b32 s22, s31, s2
	v_add_u32_e32 v140, s37, v143
	s_cselect_b32 s3, s9, s35
	s_cselect_b32 s2, s33, s34
	s_add_i32 s42, 0, 0x14000
	ds_read_b128 v[146:149], v140
	ds_read_b128 v[150:153], v140 offset:1024
	ds_read_b128 v[154:157], v140 offset:2048
	ds_read_b128 v[158:161], v140 offset:3072
	v_add_u32_e32 v140, s42, v143
	ds_read_b128 v[170:173], v140
	ds_read_b128 v[174:177], v140 offset:1024
	ds_read_b128 v[178:181], v140 offset:2048
	ds_read_b128 v[182:185], v140 offset:3072
	v_lshl_add_u64 v[140:141], s[20:21], 0, v[136:137]
	s_add_i32 m0, s17, 0xc000
	ds_read_b128 v[186:189], v145
	ds_read_b128 v[190:193], v145 offset:1024
	ds_read_b128 v[194:197], v145 offset:2048
	ds_read_b128 v[222:225], v145 offset:3072
	ds_read_b128 v[226:229], v145 offset:4096
	ds_read_b128 v[230:233], v145 offset:5120
	ds_read_b128 v[240:243], v145 offset:6144
	ds_read_b128 v[244:247], v145 offset:7168
	global_load_lds_dwordx4 v[140:141], off
	v_lshl_add_u64 v[140:141], s[20:21], 0, v[138:139]
	s_add_i32 m0, s17, 0xe000
	s_nop 0
	global_load_lds_dwordx4 v[140:141], off
	s_waitcnt vmcnt(8)
	s_waitcnt lgkmcnt(0)
	s_barrier
	s_setprio 1
	s_waitcnt lgkmcnt(0)
	v_mfma_f32_16x16x32_bf16 v[126:129], v[146:149], v[186:189], v[126:129]
	v_mfma_f32_16x16x32_bf16 v[122:125], v[154:157], v[186:189], v[122:125]
	v_mfma_f32_16x16x32_bf16 v[118:121], v[146:149], v[194:197], v[118:121]
	v_mfma_f32_16x16x32_bf16 v[110:113], v[154:157], v[194:197], v[110:113]
	v_mfma_f32_16x16x32_bf16 v[102:105], v[146:149], v[226:229], v[102:105]
	v_mfma_f32_16x16x32_bf16 v[94:97], v[154:157], v[226:229], v[94:97]
	v_mfma_f32_16x16x32_bf16 v[82:85], v[146:149], v[240:243], v[82:85]
	v_mfma_f32_16x16x32_bf16 v[74:77], v[154:157], v[240:243], v[74:77]
	v_mfma_f32_16x16x32_bf16 v[126:129], v[150:153], v[190:193], v[126:129]
	v_mfma_f32_16x16x32_bf16 v[122:125], v[158:161], v[190:193], v[122:125]
	v_mfma_f32_16x16x32_bf16 v[118:121], v[150:153], v[222:225], v[118:121]
	v_mfma_f32_16x16x32_bf16 v[110:113], v[158:161], v[222:225], v[110:113]
	v_mfma_f32_16x16x32_bf16 v[102:105], v[150:153], v[230:233], v[102:105]
	v_mfma_f32_16x16x32_bf16 v[94:97], v[158:161], v[230:233], v[94:97]
	v_mfma_f32_16x16x32_bf16 v[82:85], v[150:153], v[244:247], v[82:85]
	v_mfma_f32_16x16x32_bf16 v[74:77], v[158:161], v[244:247], v[74:77]
	s_setprio 0
	s_setprio 1
	v_mfma_f32_16x16x32_bf16 v[114:117], v[170:173], v[186:189], v[114:117]
	v_mfma_f32_16x16x32_bf16 v[106:109], v[178:181], v[186:189], v[106:109]
	v_mfma_f32_16x16x32_bf16 v[98:101], v[170:173], v[194:197], v[98:101]
	v_mfma_f32_16x16x32_bf16 v[90:93], v[178:181], v[194:197], v[90:93]
	v_mfma_f32_16x16x32_bf16 v[86:89], v[170:173], v[226:229], v[86:89]
	v_mfma_f32_16x16x32_bf16 v[78:81], v[178:181], v[226:229], v[78:81]
	v_mfma_f32_16x16x32_bf16 v[70:73], v[170:173], v[240:243], v[70:73]
	v_mfma_f32_16x16x32_bf16 v[66:69], v[178:181], v[240:243], v[66:69]
	v_mfma_f32_16x16x32_bf16 v[114:117], v[174:177], v[190:193], v[114:117]
	v_mfma_f32_16x16x32_bf16 v[106:109], v[182:185], v[190:193], v[106:109]
	v_mfma_f32_16x16x32_bf16 v[98:101], v[174:177], v[222:225], v[98:101]
	v_mfma_f32_16x16x32_bf16 v[90:93], v[182:185], v[222:225], v[90:93]
	v_mfma_f32_16x16x32_bf16 v[86:89], v[174:177], v[230:233], v[86:89]
	v_mfma_f32_16x16x32_bf16 v[78:81], v[182:185], v[230:233], v[78:81]
	v_mfma_f32_16x16x32_bf16 v[70:73], v[174:177], v[244:247], v[70:73]
	v_mfma_f32_16x16x32_bf16 v[66:69], v[182:185], v[244:247], v[66:69]
	s_setprio 0
	s_barrier
	s_add_i32 s37, s37, s25
	v_lshl_add_u64 v[140:141], s[2:3], 0, v[0:1]
	s_mov_b32 m0, s37
	ds_read_b128 v[186:189], v145 offset:16384
	ds_read_b128 v[190:193], v145 offset:17408
	ds_read_b128 v[194:197], v145 offset:18432
	ds_read_b128 v[222:225], v145 offset:19456
	ds_read_b128 v[226:229], v145 offset:20480
	ds_read_b128 v[230:233], v145 offset:21504
	ds_read_b128 v[240:243], v145 offset:22528
	ds_read_b128 v[244:247], v145 offset:23552
	global_load_lds_dwordx4 v[140:141], off
	s_add_i32 m0, s37, 0x2000
	s_add_u32 s38, s2, 0x80000
	v_lshl_add_u64 v[162:163], s[2:3], 0, v[130:131]
	s_addc_u32 s39, s3, 0
	s_add_i32 s37, s42, s25
	global_load_lds_dwordx4 v[162:163], off
	v_lshl_add_u64 v[204:205], s[38:39], 0, v[0:1]
	s_mov_b32 m0, s37
	v_lshl_add_u64 v[214:215], s[22:23], 0, v[132:133]
	global_load_lds_dwordx4 v[204:205], off
	v_lshl_add_u64 v[204:205], s[38:39], 0, v[130:131]
	s_add_i32 m0, s37, 0x2000
	s_nop 0
	global_load_lds_dwordx4 v[204:205], off
	v_lshl_add_u64 v[204:205], s[22:23], 0, v[134:135]
	s_mov_b32 m0, s17
	s_nop 0
	global_load_lds_dwordx4 v[204:205], off
	s_mov_b32 m0, s19
	s_nop 0
	global_load_lds_dwordx4 v[214:215], off
	s_waitcnt vmcnt(8)
	s_waitcnt lgkmcnt(0)
	s_barrier
; #define PG8_STAGE(bufoff, gbase, voff) do { _Pragma("unroll") for (int _i = 0; _i < 2; ++_i) \
;         __builtin_amdgcn_global_load_lds((const unsigned*)((const char*)(gbase) + (voff)[_i]), (PG8_LAS unsigned*)(lds + (bufoff) + ldsw + _i * 8192), 16, 0, 0); } while (0)
; #define PG8_LDA(dst, b, h) do { _Pragma("unroll") for (int m = 0; m < 4; ++m) _Pragma("unroll") for (int k = 0; k < 2; ++k) dst[m][k] = *(const PG8_LAS bf16x8*)(lds + PG8_SA(b, h) + aoff + m * 2048 + k * 1024); } while (0)
; #define PG8_LDB(dst, b, h) do { _Pragma("unroll") for (int n = 0; n < 2; ++n) _Pragma("unroll") for (int k = 0; k < 2; ++k) dst[n][k] = *(const PG8_LAS bf16x8*)(lds + PG8_SB(b, h) + boff + n * 2048 + k * 1024); } while (0)
; #define PG8_MMA(ai, bj, At, Bt) do { __builtin_amdgcn_s_setprio(1); _Pragma("unroll") for (int m = 0; m < 4; ++m) _Pragma("unroll") for (int n = 0; n < 2; ++n) _Pragma("unroll") for (int k = 0; k < 2; ++k) \
;         acc[ai][bj][m][n] = __builtin_amdgcn_mfma_f32_16x16x32_bf16(Bt[n][k], At[m][k], acc[ai][bj][m][n], 0, 0, 0); __builtin_amdgcn_s_setprio(0); } while (0)
; #define PG8_WAIT_V(n) asm volatile("s_waitcnt vmcnt(" #n ")" ::: "memory")
; #define PG8_WAIT_L(n) asm volatile("s_waitcnt lgkmcnt(" #n ")" ::: "memory")
; #define PG8_BAR __builtin_amdgcn_s_barrier()
; #define PG8_SCHED __builtin_amdgcn_sched_barrier(0)
; template <class Epi, class Sched, bool ALIGN_EPI = false, bool SP2 = false>
; __device__ __forceinline__ void gemm_phase(PG8_LAS unsigned char* lds, const Gemm g, const Sched& S, const Epi& E) {
;     ...
;             PG8_WAIT_V(8); PG8_WAIT_L(0); PG8_BAR; PG8_MMA(1, 0, At, B0); PG8_MMA(1, 1, At, B1); PG8_BAR; PG8_SCHED;
;             PG8_LDB(B0, 1, 0); PG8_LDB(B1, 1, 1); PG8_SCHED; PG8_LDA(At, 1, 0); PG8_STAGE(PG8_SA(0, 1), a2 + hstep, voffA);
;             PG8_WAIT_V(8); PG8_WAIT_L(0); PG8_BAR; PG8_MMA(0, 0, At, B0); PG8_MMA(0, 1, At, B1); PG8_BAR; PG8_SCHED;
	s_setprio 1
	s_waitcnt lgkmcnt(0)
	v_mfma_f32_16x16x32_bf16 v[62:65], v[146:149], v[186:189], v[62:65]
	v_mfma_f32_16x16x32_bf16 v[58:61], v[154:157], v[186:189], v[58:61]
	v_mfma_f32_16x16x32_bf16 v[54:57], v[146:149], v[194:197], v[54:57]
	v_mfma_f32_16x16x32_bf16 v[46:49], v[154:157], v[194:197], v[46:49]
	v_mfma_f32_16x16x32_bf16 v[38:41], v[146:149], v[226:229], v[38:41]
	v_mfma_f32_16x16x32_bf16 v[30:33], v[154:157], v[226:229], v[30:33]
	v_mfma_f32_16x16x32_bf16 v[22:25], v[146:149], v[240:243], v[22:25]
	v_mfma_f32_16x16x32_bf16 v[14:17], v[154:157], v[240:243], v[14:17]
	v_mfma_f32_16x16x32_bf16 v[62:65], v[150:153], v[190:193], v[62:65]
	v_mfma_f32_16x16x32_bf16 v[58:61], v[158:161], v[190:193], v[58:61]
	v_mfma_f32_16x16x32_bf16 v[54:57], v[150:153], v[222:225], v[54:57]
	v_mfma_f32_16x16x32_bf16 v[46:49], v[158:161], v[222:225], v[46:49]
	v_mfma_f32_16x16x32_bf16 v[38:41], v[150:153], v[230:233], v[38:41]
	v_mfma_f32_16x16x32_bf16 v[30:33], v[158:161], v[230:233], v[30:33]
	v_mfma_f32_16x16x32_bf16 v[22:25], v[150:153], v[244:247], v[22:25]
	v_mfma_f32_16x16x32_bf16 v[14:17], v[158:161], v[244:247], v[14:17]
	s_setprio 0
	s_setprio 1
	v_mfma_f32_16x16x32_bf16 v[50:53], v[170:173], v[186:189], v[50:53]
	v_mfma_f32_16x16x32_bf16 v[42:45], v[178:181], v[186:189], v[42:45]
	v_mfma_f32_16x16x32_bf16 v[34:37], v[170:173], v[194:197], v[34:37]
	v_mfma_f32_16x16x32_bf16 v[26:29], v[178:181], v[194:197], v[26:29]
	v_mfma_f32_16x16x32_bf16 v[18:21], v[170:173], v[226:229], v[18:21]
	v_mfma_f32_16x16x32_bf16 v[10:13], v[178:181], v[226:229], v[10:13]
	v_mfma_f32_16x16x32_bf16 v[6:9], v[170:173], v[240:243], v[6:9]
	v_mfma_f32_16x16x32_bf16 v[2:5], v[178:181], v[240:243], v[2:5]
	v_mfma_f32_16x16x32_bf16 v[50:53], v[174:177], v[190:193], v[50:53]
	v_mfma_f32_16x16x32_bf16 v[42:45], v[182:185], v[190:193], v[42:45]
	v_mfma_f32_16x16x32_bf16 v[34:37], v[174:177], v[222:225], v[34:37]
	v_mfma_f32_16x16x32_bf16 v[26:29], v[182:185], v[222:225], v[26:29]
	v_mfma_f32_16x16x32_bf16 v[18:21], v[174:177], v[230:233], v[18:21]
	v_mfma_f32_16x16x32_bf16 v[10:13], v[182:185], v[230:233], v[10:13]
	v_mfma_f32_16x16x32_bf16 v[6:9], v[174:177], v[244:247], v[6:9]
	v_mfma_f32_16x16x32_bf16 v[2:5], v[182:185], v[244:247], v[2:5]
	s_setprio 0
	s_barrier
	s_add_i32 s37, 0, 0x18000
	s_add_i32 s38, 0, 0x1c000
	v_add_u32_e32 v158, s37, v143
	v_add_u32_e32 v182, s38, v143
	ds_read_b128 v[146:149], v158
	ds_read_b128 v[150:153], v158 offset:1024
	ds_read_b128 v[154:157], v158 offset:2048
	ds_read_b128 v[158:161], v158 offset:3072
	ds_read_b128 v[170:173], v182
	ds_read_b128 v[174:177], v182 offset:1024
	ds_read_b128 v[178:181], v182 offset:2048
	ds_read_b128 v[182:185], v182 offset:3072
	s_add_u32 s22, s22, 0x80000
	s_addc_u32 s23, s23, 0
	s_mov_b32 m0, s26
	v_lshl_add_u64 v[234:235], s[22:23], 0, v[134:135]
	ds_read_b128 v[186:189], v145 offset:32768
	ds_read_b128 v[190:193], v145 offset:33792
	ds_read_b128 v[194:197], v145 offset:34816
	ds_read_b128 v[222:225], v145 offset:35840
	ds_read_b128 v[226:229], v145 offset:36864
	ds_read_b128 v[230:233], v145 offset:37888
	ds_read_b128 v[240:243], v145 offset:38912
	ds_read_b128 v[244:247], v145 offset:39936
	global_load_lds_dwordx4 v[234:235], off
	v_lshl_add_u64 v[234:235], s[22:23], 0, v[132:133]
	s_mov_b32 m0, s27
	s_nop 0
	global_load_lds_dwordx4 v[234:235], off
	s_waitcnt vmcnt(8)
	s_waitcnt lgkmcnt(0)
	s_barrier
	s_setprio 1
	s_waitcnt lgkmcnt(0)
	v_mfma_f32_16x16x32_bf16 v[126:129], v[146:149], v[186:189], v[126:129]
	v_mfma_f32_16x16x32_bf16 v[122:125], v[154:157], v[186:189], v[122:125]
	v_mfma_f32_16x16x32_bf16 v[118:121], v[146:149], v[194:197], v[118:121]
	v_mfma_f32_16x16x32_bf16 v[110:113], v[154:157], v[194:197], v[110:113]
	v_mfma_f32_16x16x32_bf16 v[102:105], v[146:149], v[226:229], v[102:105]
	v_mfma_f32_16x16x32_bf16 v[94:97], v[154:157], v[226:229], v[94:97]
	v_mfma_f32_16x16x32_bf16 v[82:85], v[146:149], v[240:243], v[82:85]
	v_mfma_f32_16x16x32_bf16 v[74:77], v[154:157], v[240:243], v[74:77]
	v_mfma_f32_16x16x32_bf16 v[126:129], v[150:153], v[190:193], v[126:129]
	v_mfma_f32_16x16x32_bf16 v[122:125], v[158:161], v[190:193], v[122:125]
	v_mfma_f32_16x16x32_bf16 v[118:121], v[150:153], v[222:225], v[118:121]
	v_mfma_f32_16x16x32_bf16 v[110:113], v[158:161], v[222:225], v[110:113]
	v_mfma_f32_16x16x32_bf16 v[102:105], v[150:153], v[230:233], v[102:105]
	v_mfma_f32_16x16x32_bf16 v[94:97], v[158:161], v[230:233], v[94:97]
	v_mfma_f32_16x16x32_bf16 v[82:85], v[150:153], v[244:247], v[82:85]
	v_mfma_f32_16x16x32_bf16 v[74:77], v[158:161], v[244:247], v[74:77]
	s_setprio 0
	s_setprio 1
	v_mfma_f32_16x16x32_bf16 v[114:117], v[170:173], v[186:189], v[114:117]
	v_mfma_f32_16x16x32_bf16 v[106:109], v[178:181], v[186:189], v[106:109]
	v_mfma_f32_16x16x32_bf16 v[98:101], v[170:173], v[194:197], v[98:101]
	v_mfma_f32_16x16x32_bf16 v[90:93], v[178:181], v[194:197], v[90:93]
	v_mfma_f32_16x16x32_bf16 v[86:89], v[170:173], v[226:229], v[86:89]
	v_mfma_f32_16x16x32_bf16 v[78:81], v[178:181], v[226:229], v[78:81]
	v_mfma_f32_16x16x32_bf16 v[70:73], v[170:173], v[240:243], v[70:73]
	v_mfma_f32_16x16x32_bf16 v[66:69], v[178:181], v[240:243], v[66:69]
	v_mfma_f32_16x16x32_bf16 v[114:117], v[174:177], v[190:193], v[114:117]
	v_mfma_f32_16x16x32_bf16 v[106:109], v[182:185], v[190:193], v[106:109]
	v_mfma_f32_16x16x32_bf16 v[98:101], v[174:177], v[222:225], v[98:101]
	v_mfma_f32_16x16x32_bf16 v[90:93], v[182:185], v[222:225], v[90:93]
	v_mfma_f32_16x16x32_bf16 v[86:89], v[174:177], v[230:233], v[86:89]
	v_mfma_f32_16x16x32_bf16 v[78:81], v[182:185], v[230:233], v[78:81]
	v_mfma_f32_16x16x32_bf16 v[70:73], v[174:177], v[244:247], v[70:73]
	v_mfma_f32_16x16x32_bf16 v[66:69], v[182:185], v[244:247], v[66:69]
	s_setprio 0
	s_barrier
; #define PG8_STAGE(bufoff, gbase, voff) do { _Pragma("unroll") for (int _i = 0; _i < 2; ++_i) \
;         __builtin_amdgcn_global_load_lds((const unsigned*)((const char*)(gbase) + (voff)[_i]), (PG8_LAS unsigned*)(lds + (bufoff) + ldsw + _i * 8192), 16, 0, 0); } while (0)
; #define PG8_LDA(dst, b, h) do { _Pragma("unroll") for (int m = 0; m < 4; ++m) _Pragma("unroll") for (int k = 0; k < 2; ++k) dst[m][k] = *(const PG8_LAS bf16x8*)(lds + PG8_SA(b, h) + aoff + m * 2048 + k * 1024); } while (0)
; #define PG8_MMA(ai, bj, At, Bt) do { __builtin_amdgcn_s_setprio(1); _Pragma("unroll") for (int m = 0; m < 4; ++m) _Pragma("unroll") for (int n = 0; n < 2; ++n) _Pragma("unroll") for (int k = 0; k < 2; ++k) \
;         acc[ai][bj][m][n] = __builtin_amdgcn_mfma_f32_16x16x32_bf16(Bt[n][k], At[m][k], acc[ai][bj][m][n], 0, 0, 0); __builtin_amdgcn_s_setprio(0); } while (0)
; #define PG8_WAIT_V(n) asm volatile("s_waitcnt vmcnt(" #n ")" ::: "memory")
; #define PG8_WAIT_L(n) asm volatile("s_waitcnt lgkmcnt(" #n ")" ::: "memory")
; #define PG8_BAR __builtin_amdgcn_s_barrier()
; #define PG8_SCHED __builtin_amdgcn_sched_barrier(0)
; template <class Epi, class Sched, bool ALIGN_EPI = false, bool SP2 = false>
; __device__ __forceinline__ void gemm_phase(PG8_LAS unsigned char* lds, const Gemm g, const Sched& S, const Epi& E) {
;     ...
;             PG8_LDA(At, 1, 1); PG8_STAGE(PG8_SB(1, 0), b3, voffB); PG8_STAGE(PG8_SB(1, 1), b3 + hstep, voffB); PG8_STAGE(PG8_SA(1, 0), a3, voffA);
;             PG8_WAIT_V(8); PG8_WAIT_L(0); PG8_BAR; PG8_MMA(1, 0, At, B0); PG8_MMA(1, 1, At, B1); PG8_BAR; PG8_SCHED;
	s_add_i32 s22, s37, s25
	v_lshl_add_u64 v[140:141], v[140:141], 0, s[46:47]
	s_mov_b32 m0, s22
	ds_read_b128 v[186:189], v145 offset:49152
	ds_read_b128 v[190:193], v145 offset:50176
	ds_read_b128 v[194:197], v145 offset:51200
	ds_read_b128 v[222:225], v145 offset:52224
	ds_read_b128 v[226:229], v145 offset:53248
	ds_read_b128 v[230:233], v145 offset:54272
	ds_read_b128 v[240:243], v145 offset:55296
	ds_read_b128 v[244:247], v145 offset:56320
	global_load_lds_dwordx4 v[140:141], off
	s_add_i32 m0, s22, 0x2000
	s_add_u32 s2, s2, 0x80080
	v_lshl_add_u64 v[140:141], v[162:163], 0, s[46:47]
	s_addc_u32 s3, s3, 0
	s_add_i32 s22, s38, s25
	global_load_lds_dwordx4 v[140:141], off
	v_lshl_add_u64 v[140:141], s[2:3], 0, v[0:1]
	s_mov_b32 m0, s22
	s_nop 0
	global_load_lds_dwordx4 v[140:141], off
	v_lshl_add_u64 v[140:141], s[2:3], 0, v[130:131]
	s_add_i32 m0, s22, 0x2000
	s_nop 0
	global_load_lds_dwordx4 v[140:141], off
	v_lshl_add_u64 v[140:141], v[204:205], 0, s[46:47]
	s_mov_b32 m0, s28
	s_nop 0
	global_load_lds_dwordx4 v[140:141], off
	v_lshl_add_u64 v[140:141], v[214:215], 0, s[46:47]
	s_mov_b32 m0, s29
	s_nop 0
	global_load_lds_dwordx4 v[140:141], off
	s_waitcnt vmcnt(8)
	s_waitcnt lgkmcnt(0)
	s_barrier
	s_setprio 1
	s_waitcnt lgkmcnt(0)
	v_mfma_f32_16x16x32_bf16 v[62:65], v[146:149], v[186:189], v[62:65]
	v_mfma_f32_16x16x32_bf16 v[58:61], v[154:157], v[186:189], v[58:61]
	v_mfma_f32_16x16x32_bf16 v[54:57], v[146:149], v[194:197], v[54:57]
	v_mfma_f32_16x16x32_bf16 v[46:49], v[154:157], v[194:197], v[46:49]
	v_mfma_f32_16x16x32_bf16 v[38:41], v[146:149], v[226:229], v[38:41]
	v_mfma_f32_16x16x32_bf16 v[30:33], v[154:157], v[226:229], v[30:33]
	v_mfma_f32_16x16x32_bf16 v[22:25], v[146:149], v[240:243], v[22:25]
	v_mfma_f32_16x16x32_bf16 v[14:17], v[154:157], v[240:243], v[14:17]
	v_mfma_f32_16x16x32_bf16 v[62:65], v[150:153], v[190:193], v[62:65]
	v_mfma_f32_16x16x32_bf16 v[58:61], v[158:161], v[190:193], v[58:61]
	v_mfma_f32_16x16x32_bf16 v[54:57], v[150:153], v[222:225], v[54:57]
	v_mfma_f32_16x16x32_bf16 v[46:49], v[158:161], v[222:225], v[46:49]
	v_mfma_f32_16x16x32_bf16 v[38:41], v[150:153], v[230:233], v[38:41]
	v_mfma_f32_16x16x32_bf16 v[30:33], v[158:161], v[230:233], v[30:33]
	v_mfma_f32_16x16x32_bf16 v[22:25], v[150:153], v[244:247], v[22:25]
	v_mfma_f32_16x16x32_bf16 v[14:17], v[158:161], v[244:247], v[14:17]
	s_setprio 0
	s_setprio 1
	v_mfma_f32_16x16x32_bf16 v[50:53], v[170:173], v[186:189], v[50:53]
	v_mfma_f32_16x16x32_bf16 v[42:45], v[178:181], v[186:189], v[42:45]
	v_mfma_f32_16x16x32_bf16 v[34:37], v[170:173], v[194:197], v[34:37]
	v_mfma_f32_16x16x32_bf16 v[26:29], v[178:181], v[194:197], v[26:29]
	v_mfma_f32_16x16x32_bf16 v[18:21], v[170:173], v[226:229], v[18:21]
	v_mfma_f32_16x16x32_bf16 v[10:13], v[178:181], v[226:229], v[10:13]
	v_mfma_f32_16x16x32_bf16 v[6:9], v[170:173], v[240:243], v[6:9]
	v_mfma_f32_16x16x32_bf16 v[2:5], v[178:181], v[240:243], v[2:5]
	v_mfma_f32_16x16x32_bf16 v[50:53], v[174:177], v[190:193], v[50:53]
	v_mfma_f32_16x16x32_bf16 v[42:45], v[182:185], v[190:193], v[42:45]
	v_mfma_f32_16x16x32_bf16 v[34:37], v[174:177], v[222:225], v[34:37]
	v_mfma_f32_16x16x32_bf16 v[26:29], v[182:185], v[222:225], v[26:29]
	v_mfma_f32_16x16x32_bf16 v[18:21], v[174:177], v[230:233], v[18:21]
	v_mfma_f32_16x16x32_bf16 v[10:13], v[182:185], v[230:233], v[10:13]
	v_mfma_f32_16x16x32_bf16 v[6:9], v[174:177], v[244:247], v[6:9]
	v_mfma_f32_16x16x32_bf16 v[2:5], v[182:185], v[244:247], v[2:5]
	s_setprio 0
	s_add_i32 s36, s36, 2
	s_add_u32 s20, s20, 0x100
	s_addc_u32 s21, s21, 0
	s_add_u32 s34, s34, 0x100
	s_addc_u32 s35, s35, 0
	s_cmp_gt_u32 s36, 29
	s_barrier
	s_cbranch_scc0 .LBB0_1346
	s_and_b64 vcc, exec, s[6:7]
	s_cbranch_vccz .LBB0_1349
	s_barrier

;     __host__ __device__ bool next(int i, Unit& u) const { if (!base.next(i >> 2, u)) return false; u.z = i & 3; return true; }
;     __host__ __device__ bool next(int i, Unit& u) const { const int L = i * G + c; if (L >= nunits) return false; const int t = L >> 2; u.z = L & 3; u.pm = t / nN; u.pn = t % nN; return true; }
; #define PG8_STAGE(bufoff, gbase, voff) do { _Pragma("unroll") for (int _i = 0; _i < 2; ++_i) \
;         __builtin_amdgcn_global_load_lds((const unsigned*)((const char*)(gbase) + (voff)[_i]), (PG8_LAS unsigned*)(lds + (bufoff) + ldsw + _i * 8192), 16, 0, 0); } while (0)
; #define PG8_LDA(dst, b, h) do { _Pragma("unroll") for (int m = 0; m < 4; ++m) _Pragma("unroll") for (int k = 0; k < 2; ++k) dst[m][k] = *(const PG8_LAS bf16x8*)(lds + PG8_SA(b, h) + aoff + m * 2048 + k * 1024); } while (0)
; #define PG8_WAIT_V(n) asm volatile("s_waitcnt vmcnt(" #n ")" ::: "memory")
; #define PG8_WAIT_L(n) asm volatile("s_waitcnt lgkmcnt(" #n ")" ::: "memory")
; template <class Epi, class Sched, bool ALIGN_EPI = false, bool SP2 = false>
; __device__ __forceinline__ void gemm_phase(PG8_LAS unsigned char* lds, const Gemm g, const Sched& S, const Epi& E) {
;     ...
;         const bool has_next = S.next(ui + 1, nxt);
;         const char* nA = has_next ? (const char*)g.A + (size_t)nxt.pm * tstep + (size_t)nxt.z * g.zA : cA; const char* nB = has_next ? (const char*)g.Bt + (size_t)nxt.pn * tstep + (size_t)nxt.z * g.zB : cB;
;         for (int t = 0; t < nt; t += 2) {
;             const bool last = (t == nt - 2);
;             const char* a1 = cA + (size_t)(t + 1) * kstep;
;             const char* a2 = last ? nA : cA + (size_t)(t + 2) * kstep; const char* b2 = last ? nB : cB + (size_t)(t + 2) * kstep;
;             const char* a3 = a2 + kstep; const char* b3 = b2 + kstep;
;             if (last && has_next) S.a_ready(nxt);
;             if constexpr (SP2) {
;             PG8_LDB(B0, 0, 0); PG8_LDB(B1, 0, 1); PG8_SCHED; PG8_LDA(At, 0, 0); PG8_STAGE(PG8_SA(1, 1), a1 + hstep, voffA);
;             PG8_WAIT_V(8); PG8_WAIT_L(0); PG8_BAR; PG8_MMA(0, 0, At, B0); PG8_MMA(0, 1, At, B1); PG8_BAR; PG8_SCHED;
;             PG8_LDA(At, 0, 1); PG8_STAGE(PG8_SB(0, 0), b2, voffB); PG8_STAGE(PG8_SB(0, 1), b2 + hstep, voffB); PG8_STAGE(PG8_SA(0, 0), a2, voffA);
;             PG8_WAIT_V(8); PG8_WAIT_L(0); PG8_BAR; PG8_MMA(1, 0, At, B0); PG8_MMA(1, 1, At, B1); PG8_BAR; PG8_SCHED;
.LBB0_1468:
	s_add_u32 s2, s20, 0xfff80080
	s_addc_u32 s3, s21, -1
	s_add_i32 s41, 0, 0x10000
	s_cmp_eq_u32 s37, 28
	s_cselect_b32 s23, s11, s3
	s_cselect_b32 s22, s33, s2
	v_add_u32_e32 v140, s41, v143
	s_cselect_b32 s3, s9, s36
	s_cselect_b32 s2, s34, s35
	s_add_i32 s44, 0, 0x14000
	ds_read_b128 v[146:149], v140
	ds_read_b128 v[150:153], v140 offset:1024
	ds_read_b128 v[154:157], v140 offset:2048
	ds_read_b128 v[158:161], v140 offset:3072
	v_add_u32_e32 v140, s44, v143
	ds_read_b128 v[170:173], v140
	ds_read_b128 v[174:177], v140 offset:1024
	ds_read_b128 v[178:181], v140 offset:2048
	ds_read_b128 v[182:185], v140 offset:3072
	v_lshl_add_u64 v[140:141], s[20:21], 0, v[136:137]
	s_add_i32 m0, s17, 0xc000
	ds_read_b128 v[186:189], v145
	ds_read_b128 v[190:193], v145 offset:1024
	ds_read_b128 v[194:197], v145 offset:2048
	ds_read_b128 v[222:225], v145 offset:3072
	ds_read_b128 v[226:229], v145 offset:4096
	ds_read_b128 v[230:233], v145 offset:5120
	ds_read_b128 v[240:243], v145 offset:6144
	ds_read_b128 v[244:247], v145 offset:7168
	global_load_lds_dwordx4 v[140:141], off
	v_lshl_add_u64 v[140:141], s[20:21], 0, v[138:139]
	s_add_i32 m0, s17, 0xe000
	s_nop 0
	global_load_lds_dwordx4 v[140:141], off
	s_waitcnt vmcnt(8)
	s_waitcnt lgkmcnt(0)
	s_barrier
	s_setprio 1
	s_waitcnt lgkmcnt(0)
	v_mfma_f32_16x16x32_bf16 v[126:129], v[146:149], v[186:189], v[126:129]
	v_mfma_f32_16x16x32_bf16 v[122:125], v[154:157], v[186:189], v[122:125]
	v_mfma_f32_16x16x32_bf16 v[110:113], v[146:149], v[194:197], v[110:113]
	v_mfma_f32_16x16x32_bf16 v[106:109], v[154:157], v[194:197], v[106:109]
	v_mfma_f32_16x16x32_bf16 v[94:97], v[146:149], v[226:229], v[94:97]
	v_mfma_f32_16x16x32_bf16 v[90:93], v[154:157], v[226:229], v[90:93]
	v_mfma_f32_16x16x32_bf16 v[78:81], v[146:149], v[240:243], v[78:81]
	v_mfma_f32_16x16x32_bf16 v[74:77], v[154:157], v[240:243], v[74:77]
	v_mfma_f32_16x16x32_bf16 v[126:129], v[150:153], v[190:193], v[126:129]
	v_mfma_f32_16x16x32_bf16 v[122:125], v[158:161], v[190:193], v[122:125]
	v_mfma_f32_16x16x32_bf16 v[110:113], v[150:153], v[222:225], v[110:113]
	v_mfma_f32_16x16x32_bf16 v[106:109], v[158:161], v[222:225], v[106:109]
	v_mfma_f32_16x16x32_bf16 v[94:97], v[150:153], v[230:233], v[94:97]
	v_mfma_f32_16x16x32_bf16 v[90:93], v[158:161], v[230:233], v[90:93]
	v_mfma_f32_16x16x32_bf16 v[78:81], v[150:153], v[244:247], v[78:81]
	v_mfma_f32_16x16x32_bf16 v[74:77], v[158:161], v[244:247], v[74:77]
	s_setprio 0
	s_setprio 1
	v_mfma_f32_16x16x32_bf16 v[118:121], v[170:173], v[186:189], v[118:121]
	v_mfma_f32_16x16x32_bf16 v[114:117], v[178:181], v[186:189], v[114:117]
	v_mfma_f32_16x16x32_bf16 v[102:105], v[170:173], v[194:197], v[102:105]
	v_mfma_f32_16x16x32_bf16 v[98:101], v[178:181], v[194:197], v[98:101]
	v_mfma_f32_16x16x32_bf16 v[86:89], v[170:173], v[226:229], v[86:89]
	v_mfma_f32_16x16x32_bf16 v[82:85], v[178:181], v[226:229], v[82:85]
	v_mfma_f32_16x16x32_bf16 v[70:73], v[170:173], v[240:243], v[70:73]
	v_mfma_f32_16x16x32_bf16 v[66:69], v[178:181], v[240:243], v[66:69]
	v_mfma_f32_16x16x32_bf16 v[118:121], v[174:177], v[190:193], v[118:121]
	v_mfma_f32_16x16x32_bf16 v[114:117], v[182:185], v[190:193], v[114:117]
	v_mfma_f32_16x16x32_bf16 v[102:105], v[174:177], v[222:225], v[102:105]
	v_mfma_f32_16x16x32_bf16 v[98:101], v[182:185], v[222:225], v[98:101]
	v_mfma_f32_16x16x32_bf16 v[86:89], v[174:177], v[230:233], v[86:89]
	v_mfma_f32_16x16x32_bf16 v[82:85], v[182:185], v[230:233], v[82:85]
	v_mfma_f32_16x16x32_bf16 v[70:73], v[174:177], v[244:247], v[70:73]
	v_mfma_f32_16x16x32_bf16 v[66:69], v[182:185], v[244:247], v[66:69]
	s_setprio 0
	s_barrier
	s_add_i32 s41, s41, s26
	v_lshl_add_u64 v[140:141], s[2:3], 0, v[0:1]
	s_mov_b32 m0, s41
	ds_read_b128 v[186:189], v145 offset:16384
	ds_read_b128 v[190:193], v145 offset:17408
	ds_read_b128 v[194:197], v145 offset:18432
	ds_read_b128 v[222:225], v145 offset:19456
	ds_read_b128 v[226:229], v145 offset:20480
	ds_read_b128 v[230:233], v145 offset:21504
	ds_read_b128 v[240:243], v145 offset:22528
	ds_read_b128 v[244:247], v145 offset:23552
	global_load_lds_dwordx4 v[140:141], off
	s_add_i32 m0, s41, 0x2000
	s_add_u32 s42, s2, 0x80000
	v_lshl_add_u64 v[162:163], s[2:3], 0, v[130:131]
	s_addc_u32 s43, s3, 0
	s_add_i32 s41, s44, s26
	global_load_lds_dwordx4 v[162:163], off
	v_lshl_add_u64 v[204:205], s[42:43], 0, v[0:1]
	s_mov_b32 m0, s41
	v_lshl_add_u64 v[214:215], s[22:23], 0, v[132:133]
	global_load_lds_dwordx4 v[204:205], off
	v_lshl_add_u64 v[204:205], s[42:43], 0, v[130:131]
	s_add_i32 m0, s41, 0x2000
	s_nop 0
	global_load_lds_dwordx4 v[204:205], off
	v_lshl_add_u64 v[204:205], s[22:23], 0, v[134:135]
	s_mov_b32 m0, s17
	s_nop 0
	global_load_lds_dwordx4 v[204:205], off
	s_mov_b32 m0, s19
	s_nop 0
	global_load_lds_dwordx4 v[214:215], off
	s_waitcnt vmcnt(8)
	s_waitcnt lgkmcnt(0)
	s_barrier
; #define PG8_STAGE(bufoff, gbase, voff) do { _Pragma("unroll") for (int _i = 0; _i < 2; ++_i) \
;         __builtin_amdgcn_global_load_lds((const unsigned*)((const char*)(gbase) + (voff)[_i]), (PG8_LAS unsigned*)(lds + (bufoff) + ldsw + _i * 8192), 16, 0, 0); } while (0)
; #define PG8_LDA(dst, b, h) do { _Pragma("unroll") for (int m = 0; m < 4; ++m) _Pragma("unroll") for (int k = 0; k < 2; ++k) dst[m][k] = *(const PG8_LAS bf16x8*)(lds + PG8_SA(b, h) + aoff + m * 2048 + k * 1024); } while (0)
; #define PG8_LDB(dst, b, h) do { _Pragma("unroll") for (int n = 0; n < 2; ++n) _Pragma("unroll") for (int k = 0; k < 2; ++k) dst[n][k] = *(const PG8_LAS bf16x8*)(lds + PG8_SB(b, h) + boff + n * 2048 + k * 1024); } while (0)
; #define PG8_MMA(ai, bj, At, Bt) do { __builtin_amdgcn_s_setprio(1); _Pragma("unroll") for (int m = 0; m < 4; ++m) _Pragma("unroll") for (int n = 0; n < 2; ++n) _Pragma("unroll") for (int k = 0; k < 2; ++k) \
;         acc[ai][bj][m][n] = __builtin_amdgcn_mfma_f32_16x16x32_bf16(Bt[n][k], At[m][k], acc[ai][bj][m][n], 0, 0, 0); __builtin_amdgcn_s_setprio(0); } while (0)
; #define PG8_WAIT_V(n) asm volatile("s_waitcnt vmcnt(" #n ")" ::: "memory")
; #define PG8_WAIT_L(n) asm volatile("s_waitcnt lgkmcnt(" #n ")" ::: "memory")
; #define PG8_BAR __builtin_amdgcn_s_barrier()
; #define PG8_SCHED __builtin_amdgcn_sched_barrier(0)
; template <class Epi, class Sched, bool ALIGN_EPI = false, bool SP2 = false>
; __device__ __forceinline__ void gemm_phase(PG8_LAS unsigned char* lds, const Gemm g, const Sched& S, const Epi& E) {
;     ...
;             PG8_WAIT_V(8); PG8_WAIT_L(0); PG8_BAR; PG8_MMA(1, 0, At, B0); PG8_MMA(1, 1, At, B1); PG8_BAR; PG8_SCHED;
;             PG8_LDB(B0, 1, 0); PG8_LDB(B1, 1, 1); PG8_SCHED; PG8_LDA(At, 1, 0); PG8_STAGE(PG8_SA(0, 1), a2 + hstep, voffA);
;             PG8_WAIT_V(8); PG8_WAIT_L(0); PG8_BAR; PG8_MMA(0, 0, At, B0); PG8_MMA(0, 1, At, B1); PG8_BAR; PG8_SCHED;
	s_setprio 1
	s_waitcnt lgkmcnt(0)
	v_mfma_f32_16x16x32_bf16 v[62:65], v[146:149], v[186:189], v[62:65]
	v_mfma_f32_16x16x32_bf16 v[58:61], v[154:157], v[186:189], v[58:61]
	v_mfma_f32_16x16x32_bf16 v[46:49], v[146:149], v[194:197], v[46:49]
	v_mfma_f32_16x16x32_bf16 v[42:45], v[154:157], v[194:197], v[42:45]
	v_mfma_f32_16x16x32_bf16 v[30:33], v[146:149], v[226:229], v[30:33]
	v_mfma_f32_16x16x32_bf16 v[26:29], v[154:157], v[226:229], v[26:29]
	v_mfma_f32_16x16x32_bf16 v[14:17], v[146:149], v[240:243], v[14:17]
	v_mfma_f32_16x16x32_bf16 v[10:13], v[154:157], v[240:243], v[10:13]
	v_mfma_f32_16x16x32_bf16 v[62:65], v[150:153], v[190:193], v[62:65]
	v_mfma_f32_16x16x32_bf16 v[58:61], v[158:161], v[190:193], v[58:61]
	v_mfma_f32_16x16x32_bf16 v[46:49], v[150:153], v[222:225], v[46:49]
	v_mfma_f32_16x16x32_bf16 v[42:45], v[158:161], v[222:225], v[42:45]
	v_mfma_f32_16x16x32_bf16 v[30:33], v[150:153], v[230:233], v[30:33]
	v_mfma_f32_16x16x32_bf16 v[26:29], v[158:161], v[230:233], v[26:29]
	v_mfma_f32_16x16x32_bf16 v[14:17], v[150:153], v[244:247], v[14:17]
	v_mfma_f32_16x16x32_bf16 v[10:13], v[158:161], v[244:247], v[10:13]
	s_setprio 0
	s_setprio 1
	v_mfma_f32_16x16x32_bf16 v[54:57], v[170:173], v[186:189], v[54:57]
	v_mfma_f32_16x16x32_bf16 v[50:53], v[178:181], v[186:189], v[50:53]
	v_mfma_f32_16x16x32_bf16 v[38:41], v[170:173], v[194:197], v[38:41]
	v_mfma_f32_16x16x32_bf16 v[34:37], v[178:181], v[194:197], v[34:37]
	v_mfma_f32_16x16x32_bf16 v[22:25], v[170:173], v[226:229], v[22:25]
	v_mfma_f32_16x16x32_bf16 v[18:21], v[178:181], v[226:229], v[18:21]
	v_mfma_f32_16x16x32_bf16 v[6:9], v[170:173], v[240:243], v[6:9]
	v_mfma_f32_16x16x32_bf16 v[2:5], v[178:181], v[240:243], v[2:5]
	v_mfma_f32_16x16x32_bf16 v[54:57], v[174:177], v[190:193], v[54:57]
	v_mfma_f32_16x16x32_bf16 v[50:53], v[182:185], v[190:193], v[50:53]
	v_mfma_f32_16x16x32_bf16 v[38:41], v[174:177], v[222:225], v[38:41]
	v_mfma_f32_16x16x32_bf16 v[34:37], v[182:185], v[222:225], v[34:37]
	v_mfma_f32_16x16x32_bf16 v[22:25], v[174:177], v[230:233], v[22:25]
	v_mfma_f32_16x16x32_bf16 v[18:21], v[182:185], v[230:233], v[18:21]
	v_mfma_f32_16x16x32_bf16 v[6:9], v[174:177], v[244:247], v[6:9]
	v_mfma_f32_16x16x32_bf16 v[2:5], v[182:185], v[244:247], v[2:5]
	s_setprio 0
	s_barrier
	s_add_i32 s41, 0, 0x18000
	s_add_i32 s42, 0, 0x1c000
	v_add_u32_e32 v158, s41, v143
	v_add_u32_e32 v182, s42, v143
	ds_read_b128 v[146:149], v158
	ds_read_b128 v[150:153], v158 offset:1024
	ds_read_b128 v[154:157], v158 offset:2048
	ds_read_b128 v[158:161], v158 offset:3072
	ds_read_b128 v[170:173], v182
	ds_read_b128 v[174:177], v182 offset:1024
	ds_read_b128 v[178:181], v182 offset:2048
	ds_read_b128 v[182:185], v182 offset:3072
	s_add_u32 s22, s22, 0x80000
	s_addc_u32 s23, s23, 0
	s_mov_b32 m0, s27
	v_lshl_add_u64 v[234:235], s[22:23], 0, v[134:135]
	ds_read_b128 v[186:189], v145 offset:32768
	ds_read_b128 v[190:193], v145 offset:33792
	ds_read_b128 v[194:197], v145 offset:34816
	ds_read_b128 v[222:225], v145 offset:35840
	ds_read_b128 v[226:229], v145 offset:36864
	ds_read_b128 v[230:233], v145 offset:37888
	ds_read_b128 v[240:243], v145 offset:38912
	ds_read_b128 v[244:247], v145 offset:39936
	global_load_lds_dwordx4 v[234:235], off
	v_lshl_add_u64 v[234:235], s[22:23], 0, v[132:133]
	s_mov_b32 m0, s28
	s_nop 0
	global_load_lds_dwordx4 v[234:235], off
	s_waitcnt vmcnt(8)
	s_waitcnt lgkmcnt(0)
	s_barrier
	s_setprio 1
	s_waitcnt lgkmcnt(0)
	v_mfma_f32_16x16x32_bf16 v[126:129], v[146:149], v[186:189], v[126:129]
	v_mfma_f32_16x16x32_bf16 v[122:125], v[154:157], v[186:189], v[122:125]
	v_mfma_f32_16x16x32_bf16 v[110:113], v[146:149], v[194:197], v[110:113]
	v_mfma_f32_16x16x32_bf16 v[106:109], v[154:157], v[194:197], v[106:109]
	v_mfma_f32_16x16x32_bf16 v[94:97], v[146:149], v[226:229], v[94:97]
	v_mfma_f32_16x16x32_bf16 v[90:93], v[154:157], v[226:229], v[90:93]
	v_mfma_f32_16x16x32_bf16 v[78:81], v[146:149], v[240:243], v[78:81]
	v_mfma_f32_16x16x32_bf16 v[74:77], v[154:157], v[240:243], v[74:77]
	v_mfma_f32_16x16x32_bf16 v[126:129], v[150:153], v[190:193], v[126:129]
	v_mfma_f32_16x16x32_bf16 v[122:125], v[158:161], v[190:193], v[122:125]
	v_mfma_f32_16x16x32_bf16 v[110:113], v[150:153], v[222:225], v[110:113]
	v_mfma_f32_16x16x32_bf16 v[106:109], v[158:161], v[222:225], v[106:109]
	v_mfma_f32_16x16x32_bf16 v[94:97], v[150:153], v[230:233], v[94:97]
	v_mfma_f32_16x16x32_bf16 v[90:93], v[158:161], v[230:233], v[90:93]
	v_mfma_f32_16x16x32_bf16 v[78:81], v[150:153], v[244:247], v[78:81]
	v_mfma_f32_16x16x32_bf16 v[74:77], v[158:161], v[244:247], v[74:77]
	s_setprio 0
	s_setprio 1
	v_mfma_f32_16x16x32_bf16 v[118:121], v[170:173], v[186:189], v[118:121]
	v_mfma_f32_16x16x32_bf16 v[114:117], v[178:181], v[186:189], v[114:117]
	v_mfma_f32_16x16x32_bf16 v[102:105], v[170:173], v[194:197], v[102:105]
	v_mfma_f32_16x16x32_bf16 v[98:101], v[178:181], v[194:197], v[98:101]
	v_mfma_f32_16x16x32_bf16 v[86:89], v[170:173], v[226:229], v[86:89]
	v_mfma_f32_16x16x32_bf16 v[82:85], v[178:181], v[226:229], v[82:85]
	v_mfma_f32_16x16x32_bf16 v[70:73], v[170:173], v[240:243], v[70:73]
	v_mfma_f32_16x16x32_bf16 v[66:69], v[178:181], v[240:243], v[66:69]
	v_mfma_f32_16x16x32_bf16 v[118:121], v[174:177], v[190:193], v[118:121]
	v_mfma_f32_16x16x32_bf16 v[114:117], v[182:185], v[190:193], v[114:117]
	v_mfma_f32_16x16x32_bf16 v[102:105], v[174:177], v[222:225], v[102:105]
	v_mfma_f32_16x16x32_bf16 v[98:101], v[182:185], v[222:225], v[98:101]
	v_mfma_f32_16x16x32_bf16 v[86:89], v[174:177], v[230:233], v[86:89]
	v_mfma_f32_16x16x32_bf16 v[82:85], v[182:185], v[230:233], v[82:85]
	v_mfma_f32_16x16x32_bf16 v[70:73], v[174:177], v[244:247], v[70:73]
	v_mfma_f32_16x16x32_bf16 v[66:69], v[182:185], v[244:247], v[66:69]
	s_setprio 0
	s_barrier
; #define PG8_STAGE(bufoff, gbase, voff) do { _Pragma("unroll") for (int _i = 0; _i < 2; ++_i) \
;         __builtin_amdgcn_global_load_lds((const unsigned*)((const char*)(gbase) + (voff)[_i]), (PG8_LAS unsigned*)(lds + (bufoff) + ldsw + _i * 8192), 16, 0, 0); } while (0)
; #define PG8_LDA(dst, b, h) do { _Pragma("unroll") for (int m = 0; m < 4; ++m) _Pragma("unroll") for (int k = 0; k < 2; ++k) dst[m][k] = *(const PG8_LAS bf16x8*)(lds + PG8_SA(b, h) + aoff + m * 2048 + k * 1024); } while (0)
; #define PG8_MMA(ai, bj, At, Bt) do { __builtin_amdgcn_s_setprio(1); _Pragma("unroll") for (int m = 0; m < 4; ++m) _Pragma("unroll") for (int n = 0; n < 2; ++n) _Pragma("unroll") for (int k = 0; k < 2; ++k) \
;         acc[ai][bj][m][n] = __builtin_amdgcn_mfma_f32_16x16x32_bf16(Bt[n][k], At[m][k], acc[ai][bj][m][n], 0, 0, 0); __builtin_amdgcn_s_setprio(0); } while (0)
; #define PG8_WAIT_V(n) asm volatile("s_waitcnt vmcnt(" #n ")" ::: "memory")
; #define PG8_WAIT_L(n) asm volatile("s_waitcnt lgkmcnt(" #n ")" ::: "memory")
; #define PG8_BAR __builtin_amdgcn_s_barrier()
; #define PG8_SCHED __builtin_amdgcn_sched_barrier(0)
; template <class Epi, class Sched, bool ALIGN_EPI = false, bool SP2 = false>
; __device__ __forceinline__ void gemm_phase(PG8_LAS unsigned char* lds, const Gemm g, const Sched& S, const Epi& E) {
;     ...
;             PG8_LDA(At, 1, 1); PG8_STAGE(PG8_SB(1, 0), b3, voffB); PG8_STAGE(PG8_SB(1, 1), b3 + hstep, voffB); PG8_STAGE(PG8_SA(1, 0), a3, voffA);
;             PG8_WAIT_V(8); PG8_WAIT_L(0); PG8_BAR; PG8_MMA(1, 0, At, B0); PG8_MMA(1, 1, At, B1); PG8_BAR; PG8_SCHED;
	s_add_i32 s22, s41, s26
	v_lshl_add_u64 v[140:141], v[140:141], 0, s[48:49]
	s_mov_b32 m0, s22
	ds_read_b128 v[186:189], v145 offset:49152
	ds_read_b128 v[190:193], v145 offset:50176
	ds_read_b128 v[194:197], v145 offset:51200
	ds_read_b128 v[222:225], v145 offset:52224
	ds_read_b128 v[226:229], v145 offset:53248
	ds_read_b128 v[230:233], v145 offset:54272
	ds_read_b128 v[240:243], v145 offset:55296
	ds_read_b128 v[244:247], v145 offset:56320
	global_load_lds_dwordx4 v[140:141], off
	s_add_i32 m0, s22, 0x2000
	s_add_u32 s2, s2, 0x80080
	v_lshl_add_u64 v[140:141], v[162:163], 0, s[48:49]
	s_addc_u32 s3, s3, 0
	s_add_i32 s22, s42, s26
	global_load_lds_dwordx4 v[140:141], off
	v_lshl_add_u64 v[140:141], s[2:3], 0, v[0:1]
	s_mov_b32 m0, s22
	s_nop 0
	global_load_lds_dwordx4 v[140:141], off
	v_lshl_add_u64 v[140:141], s[2:3], 0, v[130:131]
	s_add_i32 m0, s22, 0x2000
	s_nop 0
	global_load_lds_dwordx4 v[140:141], off
	v_lshl_add_u64 v[140:141], v[204:205], 0, s[48:49]
	s_mov_b32 m0, s29
	s_nop 0
	global_load_lds_dwordx4 v[140:141], off
	v_lshl_add_u64 v[140:141], v[214:215], 0, s[48:49]
	s_mov_b32 m0, s30
	s_nop 0
	global_load_lds_dwordx4 v[140:141], off
	s_waitcnt vmcnt(8)
	s_waitcnt lgkmcnt(0)
	s_barrier
	s_setprio 1
	s_waitcnt lgkmcnt(0)
	v_mfma_f32_16x16x32_bf16 v[62:65], v[146:149], v[186:189], v[62:65]
	v_mfma_f32_16x16x32_bf16 v[58:61], v[154:157], v[186:189], v[58:61]
	v_mfma_f32_16x16x32_bf16 v[46:49], v[146:149], v[194:197], v[46:49]
	v_mfma_f32_16x16x32_bf16 v[42:45], v[154:157], v[194:197], v[42:45]
	v_mfma_f32_16x16x32_bf16 v[30:33], v[146:149], v[226:229], v[30:33]
	v_mfma_f32_16x16x32_bf16 v[26:29], v[154:157], v[226:229], v[26:29]
	v_mfma_f32_16x16x32_bf16 v[14:17], v[146:149], v[240:243], v[14:17]
	v_mfma_f32_16x16x32_bf16 v[10:13], v[154:157], v[240:243], v[10:13]
	v_mfma_f32_16x16x32_bf16 v[62:65], v[150:153], v[190:193], v[62:65]
	v_mfma_f32_16x16x32_bf16 v[58:61], v[158:161], v[190:193], v[58:61]
	v_mfma_f32_16x16x32_bf16 v[46:49], v[150:153], v[222:225], v[46:49]
	v_mfma_f32_16x16x32_bf16 v[42:45], v[158:161], v[222:225], v[42:45]
	v_mfma_f32_16x16x32_bf16 v[30:33], v[150:153], v[230:233], v[30:33]
	v_mfma_f32_16x16x32_bf16 v[26:29], v[158:161], v[230:233], v[26:29]
	v_mfma_f32_16x16x32_bf16 v[14:17], v[150:153], v[244:247], v[14:17]
	v_mfma_f32_16x16x32_bf16 v[10:13], v[158:161], v[244:247], v[10:13]
	s_setprio 0
	s_setprio 1
	v_mfma_f32_16x16x32_bf16 v[54:57], v[170:173], v[186:189], v[54:57]
	v_mfma_f32_16x16x32_bf16 v[50:53], v[178:181], v[186:189], v[50:53]
	v_mfma_f32_16x16x32_bf16 v[38:41], v[170:173], v[194:197], v[38:41]
	v_mfma_f32_16x16x32_bf16 v[34:37], v[178:181], v[194:197], v[34:37]
	v_mfma_f32_16x16x32_bf16 v[22:25], v[170:173], v[226:229], v[22:25]
	v_mfma_f32_16x16x32_bf16 v[18:21], v[178:181], v[226:229], v[18:21]
	v_mfma_f32_16x16x32_bf16 v[6:9], v[170:173], v[240:243], v[6:9]
	v_mfma_f32_16x16x32_bf16 v[2:5], v[178:181], v[240:243], v[2:5]
	v_mfma_f32_16x16x32_bf16 v[54:57], v[174:177], v[190:193], v[54:57]
	v_mfma_f32_16x16x32_bf16 v[50:53], v[182:185], v[190:193], v[50:53]
	v_mfma_f32_16x16x32_bf16 v[38:41], v[174:177], v[222:225], v[38:41]
	v_mfma_f32_16x16x32_bf16 v[34:37], v[182:185], v[222:225], v[34:37]
	v_mfma_f32_16x16x32_bf16 v[22:25], v[174:177], v[230:233], v[22:25]
	v_mfma_f32_16x16x32_bf16 v[18:21], v[182:185], v[230:233], v[18:21]
	v_mfma_f32_16x16x32_bf16 v[6:9], v[174:177], v[244:247], v[6:9]
	v_mfma_f32_16x16x32_bf16 v[2:5], v[182:185], v[244:247], v[2:5]
	s_setprio 0
	s_add_i32 s37, s37, 2
	s_add_u32 s20, s20, 0x100
	s_addc_u32 s21, s21, 0
	s_add_u32 s35, s35, 0x100
	s_addc_u32 s36, s36, 0
	s_cmp_gt_u32 s37, 29
	s_barrier
	s_cbranch_scc0 .LBB0_1468
	s_and_b64 vcc, exec, s[6:7]
	s_cbranch_vccz .LBB0_1471
	s_barrier

;     __host__ __device__ bool next(int i, Unit& u) const { if (!base.next(i >> 2, u)) return false; u.z = i & 3; return true; }
;     __host__ __device__ bool next(int i, Unit& u) const { const int L = i * G + c; if (L >= nunits) return false; const int t = L >> 2; u.z = L & 3; u.pm = t / nN; u.pn = t % nN; return true; }
; #define PG8_STAGE(bufoff, gbase, voff) do { _Pragma("unroll") for (int _i = 0; _i < 2; ++_i) \
;         __builtin_amdgcn_global_load_lds((const unsigned*)((const char*)(gbase) + (voff)[_i]), (PG8_LAS unsigned*)(lds + (bufoff) + ldsw + _i * 8192), 16, 0, 0); } while (0)
; #define PG8_LDA(dst, b, h) do { _Pragma("unroll") for (int m = 0; m < 4; ++m) _Pragma("unroll") for (int k = 0; k < 2; ++k) dst[m][k] = *(const PG8_LAS bf16x8*)(lds + PG8_SA(b, h) + aoff + m * 2048 + k * 1024); } while (0)
; #define PG8_WAIT_V(n) asm volatile("s_waitcnt vmcnt(" #n ")" ::: "memory")
; #define PG8_WAIT_L(n) asm volatile("s_waitcnt lgkmcnt(" #n ")" ::: "memory")
; template <class Epi, class Sched, bool ALIGN_EPI = false, bool SP2 = false>
; __device__ __forceinline__ void gemm_phase(PG8_LAS unsigned char* lds, const Gemm g, const Sched& S, const Epi& E) {
;     ...
;         const bool has_next = S.next(ui + 1, nxt);
;         const char* nA = has_next ? (const char*)g.A + (size_t)nxt.pm * tstep + (size_t)nxt.z * g.zA : cA; const char* nB = has_next ? (const char*)g.Bt + (size_t)nxt.pn * tstep + (size_t)nxt.z * g.zB : cB;
;         for (int t = 0; t < nt; t += 2) {
;             const bool last = (t == nt - 2);
;             const char* a1 = cA + (size_t)(t + 1) * kstep;
;             const char* a2 = last ? nA : cA + (size_t)(t + 2) * kstep; const char* b2 = last ? nB : cB + (size_t)(t + 2) * kstep;
;             const char* a3 = a2 + kstep; const char* b3 = b2 + kstep;
;             if (last && has_next) S.a_ready(nxt);
;             if constexpr (SP2) {
;             PG8_LDB(B0, 0, 0); PG8_LDB(B1, 0, 1); PG8_SCHED; PG8_LDA(At, 0, 0); PG8_STAGE(PG8_SA(1, 1), a1 + hstep, voffA);
;             PG8_WAIT_V(8); PG8_WAIT_L(0); PG8_BAR; PG8_MMA(0, 0, At, B0); PG8_MMA(0, 1, At, B1); PG8_BAR; PG8_SCHED;
;             PG8_LDA(At, 0, 1); PG8_STAGE(PG8_SB(0, 0), b2, voffB); PG8_STAGE(PG8_SB(0, 1), b2 + hstep, voffB); PG8_STAGE(PG8_SA(0, 0), a2, voffA);
;             PG8_WAIT_V(8); PG8_WAIT_L(0); PG8_BAR; PG8_MMA(1, 0, At, B0); PG8_MMA(1, 1, At, B1); PG8_BAR; PG8_SCHED;
.LBB0_1533:
	s_add_u32 s2, s16, 0xffe00080
	s_addc_u32 s3, s17, -1
	s_add_i32 s36, 0, 0x10000
	s_cmpk_eq_i32 s35, 0x7c
	s_cselect_b32 s19, s11, s3
	s_cselect_b32 s18, s30, s2
	v_add_u32_e32 v140, s36, v143
	s_cselect_b32 s3, s9, s34
	s_cselect_b32 s2, s31, s33
	s_add_i32 s40, 0, 0x14000
	ds_read_b128 v[146:149], v140
	ds_read_b128 v[150:153], v140 offset:1024
	ds_read_b128 v[154:157], v140 offset:2048
	ds_read_b128 v[158:161], v140 offset:3072
	v_add_u32_e32 v140, s40, v143
	ds_read_b128 v[170:173], v140
	ds_read_b128 v[174:177], v140 offset:1024
	ds_read_b128 v[178:181], v140 offset:2048
	ds_read_b128 v[182:185], v140 offset:3072
	v_lshl_add_u64 v[140:141], s[16:17], 0, v[136:137]
	s_add_i32 m0, s21, 0xc000
	ds_read_b128 v[186:189], v145
	ds_read_b128 v[190:193], v145 offset:1024
	ds_read_b128 v[194:197], v145 offset:2048
	ds_read_b128 v[222:225], v145 offset:3072
	ds_read_b128 v[226:229], v145 offset:4096
	ds_read_b128 v[230:233], v145 offset:5120
	ds_read_b128 v[240:243], v145 offset:6144
	ds_read_b128 v[244:247], v145 offset:7168
	global_load_lds_dwordx4 v[140:141], off
	v_lshl_add_u64 v[140:141], s[16:17], 0, v[138:139]
	s_add_i32 m0, s21, 0xe000
	s_nop 0
	global_load_lds_dwordx4 v[140:141], off
	s_waitcnt vmcnt(8)
	s_waitcnt lgkmcnt(0)
	s_barrier
	s_setprio 1
	s_waitcnt lgkmcnt(0)
	v_mfma_f32_16x16x32_bf16 v[126:129], v[146:149], v[186:189], v[126:129]
	v_mfma_f32_16x16x32_bf16 v[122:125], v[154:157], v[186:189], v[122:125]
	v_mfma_f32_16x16x32_bf16 v[118:121], v[146:149], v[194:197], v[118:121]
	v_mfma_f32_16x16x32_bf16 v[110:113], v[154:157], v[194:197], v[110:113]
	v_mfma_f32_16x16x32_bf16 v[102:105], v[146:149], v[226:229], v[102:105]
	v_mfma_f32_16x16x32_bf16 v[94:97], v[154:157], v[226:229], v[94:97]
	v_mfma_f32_16x16x32_bf16 v[82:85], v[146:149], v[240:243], v[82:85]
	v_mfma_f32_16x16x32_bf16 v[74:77], v[154:157], v[240:243], v[74:77]
	v_mfma_f32_16x16x32_bf16 v[126:129], v[150:153], v[190:193], v[126:129]
	v_mfma_f32_16x16x32_bf16 v[122:125], v[158:161], v[190:193], v[122:125]
	v_mfma_f32_16x16x32_bf16 v[118:121], v[150:153], v[222:225], v[118:121]
	v_mfma_f32_16x16x32_bf16 v[110:113], v[158:161], v[222:225], v[110:113]
	v_mfma_f32_16x16x32_bf16 v[102:105], v[150:153], v[230:233], v[102:105]
	v_mfma_f32_16x16x32_bf16 v[94:97], v[158:161], v[230:233], v[94:97]
	v_mfma_f32_16x16x32_bf16 v[82:85], v[150:153], v[244:247], v[82:85]
	v_mfma_f32_16x16x32_bf16 v[74:77], v[158:161], v[244:247], v[74:77]
	s_setprio 0
	s_setprio 1
	v_mfma_f32_16x16x32_bf16 v[114:117], v[170:173], v[186:189], v[114:117]
	v_mfma_f32_16x16x32_bf16 v[106:109], v[178:181], v[186:189], v[106:109]
	v_mfma_f32_16x16x32_bf16 v[98:101], v[170:173], v[194:197], v[98:101]
	v_mfma_f32_16x16x32_bf16 v[90:93], v[178:181], v[194:197], v[90:93]
	v_mfma_f32_16x16x32_bf16 v[86:89], v[170:173], v[226:229], v[86:89]
	v_mfma_f32_16x16x32_bf16 v[78:81], v[178:181], v[226:229], v[78:81]
	v_mfma_f32_16x16x32_bf16 v[70:73], v[170:173], v[240:243], v[70:73]
	v_mfma_f32_16x16x32_bf16 v[66:69], v[178:181], v[240:243], v[66:69]
	v_mfma_f32_16x16x32_bf16 v[114:117], v[174:177], v[190:193], v[114:117]
	v_mfma_f32_16x16x32_bf16 v[106:109], v[182:185], v[190:193], v[106:109]
	v_mfma_f32_16x16x32_bf16 v[98:101], v[174:177], v[222:225], v[98:101]
	v_mfma_f32_16x16x32_bf16 v[90:93], v[182:185], v[222:225], v[90:93]
	v_mfma_f32_16x16x32_bf16 v[86:89], v[174:177], v[230:233], v[86:89]
	v_mfma_f32_16x16x32_bf16 v[78:81], v[182:185], v[230:233], v[78:81]
	v_mfma_f32_16x16x32_bf16 v[70:73], v[174:177], v[244:247], v[70:73]
	v_mfma_f32_16x16x32_bf16 v[66:69], v[182:185], v[244:247], v[66:69]
	s_setprio 0
	s_barrier
	s_add_i32 s36, s36, s20
	v_lshl_add_u64 v[140:141], s[2:3], 0, v[0:1]
	s_mov_b32 m0, s36
	ds_read_b128 v[186:189], v145 offset:16384
	ds_read_b128 v[190:193], v145 offset:17408
	ds_read_b128 v[194:197], v145 offset:18432
	ds_read_b128 v[222:225], v145 offset:19456
	ds_read_b128 v[226:229], v145 offset:20480
	ds_read_b128 v[230:233], v145 offset:21504
	ds_read_b128 v[240:243], v145 offset:22528
	ds_read_b128 v[244:247], v145 offset:23552
	global_load_lds_dwordx4 v[140:141], off
	s_add_i32 m0, s36, 0x2000
	s_add_u32 s36, s2, 0x200000
	v_lshl_add_u64 v[162:163], s[2:3], 0, v[130:131]
	s_addc_u32 s37, s3, 0
	s_add_i32 s40, s40, s20
	global_load_lds_dwordx4 v[162:163], off
	v_lshl_add_u64 v[204:205], s[36:37], 0, v[0:1]
	s_mov_b32 m0, s40
	v_lshl_add_u64 v[214:215], s[18:19], 0, v[132:133]
	global_load_lds_dwordx4 v[204:205], off
	v_lshl_add_u64 v[204:205], s[36:37], 0, v[130:131]
	s_add_i32 m0, s40, 0x2000
	s_nop 0
	global_load_lds_dwordx4 v[204:205], off
	v_lshl_add_u64 v[204:205], s[18:19], 0, v[134:135]
	s_mov_b32 m0, s21
	s_nop 0
	global_load_lds_dwordx4 v[204:205], off
	s_mov_b32 m0, s22
	s_nop 0
	global_load_lds_dwordx4 v[214:215], off
	s_waitcnt vmcnt(8)
	s_waitcnt lgkmcnt(0)
	s_barrier
; #define PG8_STAGE(bufoff, gbase, voff) do { _Pragma("unroll") for (int _i = 0; _i < 2; ++_i) \
;         __builtin_amdgcn_global_load_lds((const unsigned*)((const char*)(gbase) + (voff)[_i]), (PG8_LAS unsigned*)(lds + (bufoff) + ldsw + _i * 8192), 16, 0, 0); } while (0)
; #define PG8_LDA(dst, b, h) do { _Pragma("unroll") for (int m = 0; m < 4; ++m) _Pragma("unroll") for (int k = 0; k < 2; ++k) dst[m][k] = *(const PG8_LAS bf16x8*)(lds + PG8_SA(b, h) + aoff + m * 2048 + k * 1024); } while (0)
; #define PG8_LDB(dst, b, h) do { _Pragma("unroll") for (int n = 0; n < 2; ++n) _Pragma("unroll") for (int k = 0; k < 2; ++k) dst[n][k] = *(const PG8_LAS bf16x8*)(lds + PG8_SB(b, h) + boff + n * 2048 + k * 1024); } while (0)
; #define PG8_MMA(ai, bj, At, Bt) do { __builtin_amdgcn_s_setprio(1); _Pragma("unroll") for (int m = 0; m < 4; ++m) _Pragma("unroll") for (int n = 0; n < 2; ++n) _Pragma("unroll") for (int k = 0; k < 2; ++k) \
;         acc[ai][bj][m][n] = __builtin_amdgcn_mfma_f32_16x16x32_bf16(Bt[n][k], At[m][k], acc[ai][bj][m][n], 0, 0, 0); __builtin_amdgcn_s_setprio(0); } while (0)
; #define PG8_WAIT_V(n) asm volatile("s_waitcnt vmcnt(" #n ")" ::: "memory")
; #define PG8_WAIT_L(n) asm volatile("s_waitcnt lgkmcnt(" #n ")" ::: "memory")
; #define PG8_BAR __builtin_amdgcn_s_barrier()
; #define PG8_SCHED __builtin_amdgcn_sched_barrier(0)
; template <class Epi, class Sched, bool ALIGN_EPI = false, bool SP2 = false>
; __device__ __forceinline__ void gemm_phase(PG8_LAS unsigned char* lds, const Gemm g, const Sched& S, const Epi& E) {
;     ...
;             PG8_WAIT_V(8); PG8_WAIT_L(0); PG8_BAR; PG8_MMA(1, 0, At, B0); PG8_MMA(1, 1, At, B1); PG8_BAR; PG8_SCHED;
;             PG8_LDB(B0, 1, 0); PG8_LDB(B1, 1, 1); PG8_SCHED; PG8_LDA(At, 1, 0); PG8_STAGE(PG8_SA(0, 1), a2 + hstep, voffA);
;             PG8_WAIT_V(8); PG8_WAIT_L(0); PG8_BAR; PG8_MMA(0, 0, At, B0); PG8_MMA(0, 1, At, B1); PG8_BAR; PG8_SCHED;
	s_setprio 1
	s_waitcnt lgkmcnt(0)
	v_mfma_f32_16x16x32_bf16 v[62:65], v[146:149], v[186:189], v[62:65]
	v_mfma_f32_16x16x32_bf16 v[58:61], v[154:157], v[186:189], v[58:61]
	v_mfma_f32_16x16x32_bf16 v[54:57], v[146:149], v[194:197], v[54:57]
	v_mfma_f32_16x16x32_bf16 v[46:49], v[154:157], v[194:197], v[46:49]
	v_mfma_f32_16x16x32_bf16 v[38:41], v[146:149], v[226:229], v[38:41]
	v_mfma_f32_16x16x32_bf16 v[30:33], v[154:157], v[226:229], v[30:33]
	v_mfma_f32_16x16x32_bf16 v[22:25], v[146:149], v[240:243], v[22:25]
	v_mfma_f32_16x16x32_bf16 v[14:17], v[154:157], v[240:243], v[14:17]
	v_mfma_f32_16x16x32_bf16 v[62:65], v[150:153], v[190:193], v[62:65]
	v_mfma_f32_16x16x32_bf16 v[58:61], v[158:161], v[190:193], v[58:61]
	v_mfma_f32_16x16x32_bf16 v[54:57], v[150:153], v[222:225], v[54:57]
	v_mfma_f32_16x16x32_bf16 v[46:49], v[158:161], v[222:225], v[46:49]
	v_mfma_f32_16x16x32_bf16 v[38:41], v[150:153], v[230:233], v[38:41]
	v_mfma_f32_16x16x32_bf16 v[30:33], v[158:161], v[230:233], v[30:33]
	v_mfma_f32_16x16x32_bf16 v[22:25], v[150:153], v[244:247], v[22:25]
	v_mfma_f32_16x16x32_bf16 v[14:17], v[158:161], v[244:247], v[14:17]
	s_setprio 0
	s_setprio 1
	v_mfma_f32_16x16x32_bf16 v[50:53], v[170:173], v[186:189], v[50:53]
	v_mfma_f32_16x16x32_bf16 v[42:45], v[178:181], v[186:189], v[42:45]
	v_mfma_f32_16x16x32_bf16 v[34:37], v[170:173], v[194:197], v[34:37]
	v_mfma_f32_16x16x32_bf16 v[26:29], v[178:181], v[194:197], v[26:29]
	v_mfma_f32_16x16x32_bf16 v[18:21], v[170:173], v[226:229], v[18:21]
	v_mfma_f32_16x16x32_bf16 v[10:13], v[178:181], v[226:229], v[10:13]
	v_mfma_f32_16x16x32_bf16 v[6:9], v[170:173], v[240:243], v[6:9]
	v_mfma_f32_16x16x32_bf16 v[2:5], v[178:181], v[240:243], v[2:5]
	v_mfma_f32_16x16x32_bf16 v[50:53], v[174:177], v[190:193], v[50:53]
	v_mfma_f32_16x16x32_bf16 v[42:45], v[182:185], v[190:193], v[42:45]
	v_mfma_f32_16x16x32_bf16 v[34:37], v[174:177], v[222:225], v[34:37]
	v_mfma_f32_16x16x32_bf16 v[26:29], v[182:185], v[222:225], v[26:29]
	v_mfma_f32_16x16x32_bf16 v[18:21], v[174:177], v[230:233], v[18:21]
	v_mfma_f32_16x16x32_bf16 v[10:13], v[182:185], v[230:233], v[10:13]
	v_mfma_f32_16x16x32_bf16 v[6:9], v[174:177], v[244:247], v[6:9]
	v_mfma_f32_16x16x32_bf16 v[2:5], v[182:185], v[244:247], v[2:5]
	s_setprio 0
	s_barrier
	s_add_i32 s36, 0, 0x18000
	s_add_i32 s37, 0, 0x1c000
	v_add_u32_e32 v158, s36, v143
	v_add_u32_e32 v182, s37, v143
	ds_read_b128 v[146:149], v158
	ds_read_b128 v[150:153], v158 offset:1024
	ds_read_b128 v[154:157], v158 offset:2048
	ds_read_b128 v[158:161], v158 offset:3072
	ds_read_b128 v[170:173], v182
	ds_read_b128 v[174:177], v182 offset:1024
	ds_read_b128 v[178:181], v182 offset:2048
	ds_read_b128 v[182:185], v182 offset:3072
	s_add_u32 s18, s18, 0x200000
	s_addc_u32 s19, s19, 0
	s_mov_b32 m0, s23
	v_lshl_add_u64 v[234:235], s[18:19], 0, v[134:135]
	ds_read_b128 v[186:189], v145 offset:32768
	ds_read_b128 v[190:193], v145 offset:33792
	ds_read_b128 v[194:197], v145 offset:34816
	ds_read_b128 v[222:225], v145 offset:35840
	ds_read_b128 v[226:229], v145 offset:36864
	ds_read_b128 v[230:233], v145 offset:37888
	ds_read_b128 v[240:243], v145 offset:38912
	ds_read_b128 v[244:247], v145 offset:39936
	global_load_lds_dwordx4 v[234:235], off
	v_lshl_add_u64 v[234:235], s[18:19], 0, v[132:133]
	s_mov_b32 m0, s24
	s_nop 0
	global_load_lds_dwordx4 v[234:235], off
	s_waitcnt vmcnt(8)
	s_waitcnt lgkmcnt(0)
	s_barrier
	s_setprio 1
	s_waitcnt lgkmcnt(0)
	v_mfma_f32_16x16x32_bf16 v[126:129], v[146:149], v[186:189], v[126:129]
	v_mfma_f32_16x16x32_bf16 v[122:125], v[154:157], v[186:189], v[122:125]
	v_mfma_f32_16x16x32_bf16 v[118:121], v[146:149], v[194:197], v[118:121]
	v_mfma_f32_16x16x32_bf16 v[110:113], v[154:157], v[194:197], v[110:113]
	v_mfma_f32_16x16x32_bf16 v[102:105], v[146:149], v[226:229], v[102:105]
	v_mfma_f32_16x16x32_bf16 v[94:97], v[154:157], v[226:229], v[94:97]
	v_mfma_f32_16x16x32_bf16 v[82:85], v[146:149], v[240:243], v[82:85]
	v_mfma_f32_16x16x32_bf16 v[74:77], v[154:157], v[240:243], v[74:77]
	v_mfma_f32_16x16x32_bf16 v[126:129], v[150:153], v[190:193], v[126:129]
	v_mfma_f32_16x16x32_bf16 v[122:125], v[158:161], v[190:193], v[122:125]
	v_mfma_f32_16x16x32_bf16 v[118:121], v[150:153], v[222:225], v[118:121]
	v_mfma_f32_16x16x32_bf16 v[110:113], v[158:161], v[222:225], v[110:113]
	v_mfma_f32_16x16x32_bf16 v[102:105], v[150:153], v[230:233], v[102:105]
	v_mfma_f32_16x16x32_bf16 v[94:97], v[158:161], v[230:233], v[94:97]
	v_mfma_f32_16x16x32_bf16 v[82:85], v[150:153], v[244:247], v[82:85]
	v_mfma_f32_16x16x32_bf16 v[74:77], v[158:161], v[244:247], v[74:77]
	s_setprio 0
	s_setprio 1
	v_mfma_f32_16x16x32_bf16 v[114:117], v[170:173], v[186:189], v[114:117]
	v_mfma_f32_16x16x32_bf16 v[106:109], v[178:181], v[186:189], v[106:109]
	v_mfma_f32_16x16x32_bf16 v[98:101], v[170:173], v[194:197], v[98:101]
	v_mfma_f32_16x16x32_bf16 v[90:93], v[178:181], v[194:197], v[90:93]
	v_mfma_f32_16x16x32_bf16 v[86:89], v[170:173], v[226:229], v[86:89]
	v_mfma_f32_16x16x32_bf16 v[78:81], v[178:181], v[226:229], v[78:81]
	v_mfma_f32_16x16x32_bf16 v[70:73], v[170:173], v[240:243], v[70:73]
	v_mfma_f32_16x16x32_bf16 v[66:69], v[178:181], v[240:243], v[66:69]
	v_mfma_f32_16x16x32_bf16 v[114:117], v[174:177], v[190:193], v[114:117]
	v_mfma_f32_16x16x32_bf16 v[106:109], v[182:185], v[190:193], v[106:109]
	v_mfma_f32_16x16x32_bf16 v[98:101], v[174:177], v[222:225], v[98:101]
	v_mfma_f32_16x16x32_bf16 v[90:93], v[182:185], v[222:225], v[90:93]
	v_mfma_f32_16x16x32_bf16 v[86:89], v[174:177], v[230:233], v[86:89]
	v_mfma_f32_16x16x32_bf16 v[78:81], v[182:185], v[230:233], v[78:81]
	v_mfma_f32_16x16x32_bf16 v[70:73], v[174:177], v[244:247], v[70:73]
	v_mfma_f32_16x16x32_bf16 v[66:69], v[182:185], v[244:247], v[66:69]
	s_setprio 0
	s_barrier
; #define PG8_STAGE(bufoff, gbase, voff) do { _Pragma("unroll") for (int _i = 0; _i < 2; ++_i) \
;         __builtin_amdgcn_global_load_lds((const unsigned*)((const char*)(gbase) + (voff)[_i]), (PG8_LAS unsigned*)(lds + (bufoff) + ldsw + _i * 8192), 16, 0, 0); } while (0)
; #define PG8_LDA(dst, b, h) do { _Pragma("unroll") for (int m = 0; m < 4; ++m) _Pragma("unroll") for (int k = 0; k < 2; ++k) dst[m][k] = *(const PG8_LAS bf16x8*)(lds + PG8_SA(b, h) + aoff + m * 2048 + k * 1024); } while (0)
; #define PG8_MMA(ai, bj, At, Bt) do { __builtin_amdgcn_s_setprio(1); _Pragma("unroll") for (int m = 0; m < 4; ++m) _Pragma("unroll") for (int n = 0; n < 2; ++n) _Pragma("unroll") for (int k = 0; k < 2; ++k) \
;         acc[ai][bj][m][n] = __builtin_amdgcn_mfma_f32_16x16x32_bf16(Bt[n][k], At[m][k], acc[ai][bj][m][n], 0, 0, 0); __builtin_amdgcn_s_setprio(0); } while (0)
; #define PG8_WAIT_V(n) asm volatile("s_waitcnt vmcnt(" #n ")" ::: "memory")
; #define PG8_WAIT_L(n) asm volatile("s_waitcnt lgkmcnt(" #n ")" ::: "memory")
; #define PG8_BAR __builtin_amdgcn_s_barrier()
; #define PG8_SCHED __builtin_amdgcn_sched_barrier(0)
; template <class Epi, class Sched, bool ALIGN_EPI = false, bool SP2 = false>
; __device__ __forceinline__ void gemm_phase(PG8_LAS unsigned char* lds, const Gemm g, const Sched& S, const Epi& E) {
;     ...
;             PG8_LDA(At, 1, 1); PG8_STAGE(PG8_SB(1, 0), b3, voffB); PG8_STAGE(PG8_SB(1, 1), b3 + hstep, voffB); PG8_STAGE(PG8_SA(1, 0), a3, voffA);
;             PG8_WAIT_V(8); PG8_WAIT_L(0); PG8_BAR; PG8_MMA(1, 0, At, B0); PG8_MMA(1, 1, At, B1); PG8_BAR; PG8_SCHED;
	s_add_i32 s18, s36, s20
	v_lshl_add_u64 v[140:141], v[140:141], 0, s[48:49]
	s_mov_b32 m0, s18
	ds_read_b128 v[186:189], v145 offset:49152
	ds_read_b128 v[190:193], v145 offset:50176
	ds_read_b128 v[194:197], v145 offset:51200
	ds_read_b128 v[222:225], v145 offset:52224
	ds_read_b128 v[226:229], v145 offset:53248
	ds_read_b128 v[230:233], v145 offset:54272
	ds_read_b128 v[240:243], v145 offset:55296
	ds_read_b128 v[244:247], v145 offset:56320
	global_load_lds_dwordx4 v[140:141], off
	s_add_i32 m0, s18, 0x2000
	s_add_u32 s2, s2, 0x200080
	v_lshl_add_u64 v[140:141], v[162:163], 0, s[48:49]
	s_addc_u32 s3, s3, 0
	s_add_i32 s18, s37, s20
	global_load_lds_dwordx4 v[140:141], off
	v_lshl_add_u64 v[140:141], s[2:3], 0, v[0:1]
	s_mov_b32 m0, s18
	s_nop 0
	global_load_lds_dwordx4 v[140:141], off
	v_lshl_add_u64 v[140:141], s[2:3], 0, v[130:131]
	s_add_i32 m0, s18, 0x2000
	s_nop 0
	global_load_lds_dwordx4 v[140:141], off
	v_lshl_add_u64 v[140:141], v[204:205], 0, s[48:49]
	s_mov_b32 m0, s25
	s_nop 0
	global_load_lds_dwordx4 v[140:141], off
	v_lshl_add_u64 v[140:141], v[214:215], 0, s[48:49]
	s_mov_b32 m0, s26
	s_nop 0
	global_load_lds_dwordx4 v[140:141], off
	s_waitcnt vmcnt(8)
	s_waitcnt lgkmcnt(0)
	s_barrier
	s_setprio 1
	s_waitcnt lgkmcnt(0)
	v_mfma_f32_16x16x32_bf16 v[62:65], v[146:149], v[186:189], v[62:65]
	v_mfma_f32_16x16x32_bf16 v[58:61], v[154:157], v[186:189], v[58:61]
	v_mfma_f32_16x16x32_bf16 v[54:57], v[146:149], v[194:197], v[54:57]
	v_mfma_f32_16x16x32_bf16 v[46:49], v[154:157], v[194:197], v[46:49]
	v_mfma_f32_16x16x32_bf16 v[38:41], v[146:149], v[226:229], v[38:41]
	v_mfma_f32_16x16x32_bf16 v[30:33], v[154:157], v[226:229], v[30:33]
	v_mfma_f32_16x16x32_bf16 v[22:25], v[146:149], v[240:243], v[22:25]
	v_mfma_f32_16x16x32_bf16 v[14:17], v[154:157], v[240:243], v[14:17]
	v_mfma_f32_16x16x32_bf16 v[62:65], v[150:153], v[190:193], v[62:65]
	v_mfma_f32_16x16x32_bf16 v[58:61], v[158:161], v[190:193], v[58:61]
	v_mfma_f32_16x16x32_bf16 v[54:57], v[150:153], v[222:225], v[54:57]
	v_mfma_f32_16x16x32_bf16 v[46:49], v[158:161], v[222:225], v[46:49]
	v_mfma_f32_16x16x32_bf16 v[38:41], v[150:153], v[230:233], v[38:41]
	v_mfma_f32_16x16x32_bf16 v[30:33], v[158:161], v[230:233], v[30:33]
	v_mfma_f32_16x16x32_bf16 v[22:25], v[150:153], v[244:247], v[22:25]
	v_mfma_f32_16x16x32_bf16 v[14:17], v[158:161], v[244:247], v[14:17]
	s_setprio 0
	s_setprio 1
	v_mfma_f32_16x16x32_bf16 v[50:53], v[170:173], v[186:189], v[50:53]
	v_mfma_f32_16x16x32_bf16 v[42:45], v[178:181], v[186:189], v[42:45]
	v_mfma_f32_16x16x32_bf16 v[34:37], v[170:173], v[194:197], v[34:37]
	v_mfma_f32_16x16x32_bf16 v[26:29], v[178:181], v[194:197], v[26:29]
	v_mfma_f32_16x16x32_bf16 v[18:21], v[170:173], v[226:229], v[18:21]
	v_mfma_f32_16x16x32_bf16 v[10:13], v[178:181], v[226:229], v[10:13]
	v_mfma_f32_16x16x32_bf16 v[6:9], v[170:173], v[240:243], v[6:9]
	v_mfma_f32_16x16x32_bf16 v[2:5], v[178:181], v[240:243], v[2:5]
	v_mfma_f32_16x16x32_bf16 v[50:53], v[174:177], v[190:193], v[50:53]
	v_mfma_f32_16x16x32_bf16 v[42:45], v[182:185], v[190:193], v[42:45]
	v_mfma_f32_16x16x32_bf16 v[34:37], v[174:177], v[222:225], v[34:37]
	v_mfma_f32_16x16x32_bf16 v[26:29], v[182:185], v[222:225], v[26:29]
	v_mfma_f32_16x16x32_bf16 v[18:21], v[174:177], v[230:233], v[18:21]
	v_mfma_f32_16x16x32_bf16 v[10:13], v[182:185], v[230:233], v[10:13]
	v_mfma_f32_16x16x32_bf16 v[6:9], v[174:177], v[244:247], v[6:9]
	v_mfma_f32_16x16x32_bf16 v[2:5], v[182:185], v[244:247], v[2:5]
	s_setprio 0
	s_add_i32 s35, s35, 2
	s_add_u32 s16, s16, 0x100
	s_addc_u32 s17, s17, 0
	s_add_u32 s33, s33, 0x100
	s_addc_u32 s34, s34, 0
	s_cmpk_gt_u32 s35, 0x7d
	s_barrier
	s_cbranch_scc0 .LBB0_1533
	s_and_b64 vcc, exec, s[6:7]
	v_readlane_b32 s33, v254, 33
	s_cbranch_vccz .LBB0_1536
	s_barrier

;     __host__ __device__ bool next(int i, Unit& u) const { if (!base.next(i >> 2, u)) return false; u.z = i & 3; return true; }
;     __host__ __device__ bool next(int i, Unit& u) const { const int L = i * G + c; if (L >= nunits) return false; const int t = L >> 2; u.z = L & 3; u.pm = t / nN; u.pn = t % nN; return true; }
; #define PG8_STAGE(bufoff, gbase, voff) do { _Pragma("unroll") for (int _i = 0; _i < 2; ++_i) \
;         __builtin_amdgcn_global_load_lds((const unsigned*)((const char*)(gbase) + (voff)[_i]), (PG8_LAS unsigned*)(lds + (bufoff) + ldsw + _i * 8192), 16, 0, 0); } while (0)
; #define PG8_LDA(dst, b, h) do { _Pragma("unroll") for (int m = 0; m < 4; ++m) _Pragma("unroll") for (int k = 0; k < 2; ++k) dst[m][k] = *(const PG8_LAS bf16x8*)(lds + PG8_SA(b, h) + aoff + m * 2048 + k * 1024); } while (0)
; #define PG8_WAIT_V(n) asm volatile("s_waitcnt vmcnt(" #n ")" ::: "memory")
; #define PG8_WAIT_L(n) asm volatile("s_waitcnt lgkmcnt(" #n ")" ::: "memory")
; template <class Epi, class Sched, bool ALIGN_EPI = false, bool SP2 = false>
; __device__ __forceinline__ void gemm_phase(PG8_LAS unsigned char* lds, const Gemm g, const Sched& S, const Epi& E) {
;     ...
;         const bool has_next = S.next(ui + 1, nxt);
;         const char* nA = has_next ? (const char*)g.A + (size_t)nxt.pm * tstep + (size_t)nxt.z * g.zA : cA; const char* nB = has_next ? (const char*)g.Bt + (size_t)nxt.pn * tstep + (size_t)nxt.z * g.zB : cB;
;         for (int t = 0; t < nt; t += 2) {
;             const bool last = (t == nt - 2);
;             const char* a1 = cA + (size_t)(t + 1) * kstep;
;             const char* a2 = last ? nA : cA + (size_t)(t + 2) * kstep; const char* b2 = last ? nB : cB + (size_t)(t + 2) * kstep;
;             const char* a3 = a2 + kstep; const char* b3 = b2 + kstep;
;             if (last && has_next) S.a_ready(nxt);
;             if constexpr (SP2) {
;             PG8_LDB(B0, 0, 0); PG8_LDB(B1, 0, 1); PG8_SCHED; PG8_LDA(At, 0, 0); PG8_STAGE(PG8_SA(1, 1), a1 + hstep, voffA);
;             PG8_WAIT_V(8); PG8_WAIT_L(0); PG8_BAR; PG8_MMA(0, 0, At, B0); PG8_MMA(0, 1, At, B1); PG8_BAR; PG8_SCHED;
;             PG8_LDA(At, 0, 1); PG8_STAGE(PG8_SB(0, 0), b2, voffB); PG8_STAGE(PG8_SB(0, 1), b2 + hstep, voffB); PG8_STAGE(PG8_SA(0, 0), a2, voffA);
;             PG8_WAIT_V(8); PG8_WAIT_L(0); PG8_BAR; PG8_MMA(1, 0, At, B0); PG8_MMA(1, 1, At, B1); PG8_BAR; PG8_SCHED;
.LBB0_1550:
	s_add_u32 s2, s18, 0xffe00080
	s_addc_u32 s3, s19, -1
	s_add_i32 s37, 0, 0x10000
	s_cmp_eq_u32 s36, 28
	s_cselect_b32 s21, s7, s3
	s_cselect_b32 s20, s9, s2
	s_cselect_b32 s3, s11, s35
	s_cselect_b32 s2, s33, s34
	s_add_i32 s42, 0, 0x14000
	v_add_u32_e32 v156, s37, v141
	v_add_u32_e32 v178, s42, v141
	ds_read_b128 v[144:147], v156
	ds_read_b128 v[148:151], v156 offset:1024
	ds_read_b128 v[152:155], v156 offset:2048
	ds_read_b128 v[156:159], v156 offset:3072
	ds_read_b128 v[160:163], v178
	ds_read_b128 v[170:173], v178 offset:1024
	ds_read_b128 v[174:177], v178 offset:2048
	ds_read_b128 v[178:181], v178 offset:3072
	v_lshl_add_u64 v[204:205], s[18:19], 0, v[136:137]
	s_add_i32 m0, s23, 0xc000
	ds_read_b128 v[182:185], v143
	ds_read_b128 v[186:189], v143 offset:1024
	ds_read_b128 v[190:193], v143 offset:2048
	ds_read_b128 v[194:197], v143 offset:3072
	ds_read_b128 v[222:225], v143 offset:4096
	ds_read_b128 v[226:229], v143 offset:5120
	ds_read_b128 v[230:233], v143 offset:6144
	ds_read_b128 v[240:243], v143 offset:7168
	global_load_lds_dwordx4 v[204:205], off
	v_lshl_add_u64 v[204:205], s[18:19], 0, v[138:139]
	s_add_i32 m0, s23, 0xe000
	s_nop 0
	global_load_lds_dwordx4 v[204:205], off
	s_waitcnt vmcnt(8)
	s_waitcnt lgkmcnt(0)
	s_barrier
	s_setprio 1
	s_waitcnt lgkmcnt(0)
	v_mfma_f32_16x16x32_bf16 v[126:129], v[144:147], v[182:185], v[126:129]
	v_mfma_f32_16x16x32_bf16 v[122:125], v[152:155], v[182:185], v[122:125]
	v_mfma_f32_16x16x32_bf16 v[118:121], v[144:147], v[190:193], v[118:121]
	v_mfma_f32_16x16x32_bf16 v[114:117], v[152:155], v[190:193], v[114:117]
	v_mfma_f32_16x16x32_bf16 v[102:105], v[144:147], v[222:225], v[102:105]
	v_mfma_f32_16x16x32_bf16 v[98:101], v[152:155], v[222:225], v[98:101]
	v_mfma_f32_16x16x32_bf16 v[86:89], v[144:147], v[230:233], v[86:89]
	v_mfma_f32_16x16x32_bf16 v[82:85], v[152:155], v[230:233], v[82:85]
	v_mfma_f32_16x16x32_bf16 v[126:129], v[148:151], v[186:189], v[126:129]
	v_mfma_f32_16x16x32_bf16 v[122:125], v[156:159], v[186:189], v[122:125]
	v_mfma_f32_16x16x32_bf16 v[118:121], v[148:151], v[194:197], v[118:121]
	v_mfma_f32_16x16x32_bf16 v[114:117], v[156:159], v[194:197], v[114:117]
	v_mfma_f32_16x16x32_bf16 v[102:105], v[148:151], v[226:229], v[102:105]
	v_mfma_f32_16x16x32_bf16 v[98:101], v[156:159], v[226:229], v[98:101]
	v_mfma_f32_16x16x32_bf16 v[86:89], v[148:151], v[240:243], v[86:89]
	v_mfma_f32_16x16x32_bf16 v[82:85], v[156:159], v[240:243], v[82:85]
	s_setprio 0
	s_setprio 1
	v_mfma_f32_16x16x32_bf16 v[110:113], v[160:163], v[182:185], v[110:113]
	v_mfma_f32_16x16x32_bf16 v[106:109], v[174:177], v[182:185], v[106:109]
	v_mfma_f32_16x16x32_bf16 v[94:97], v[160:163], v[190:193], v[94:97]
	v_mfma_f32_16x16x32_bf16 v[90:93], v[174:177], v[190:193], v[90:93]
	v_mfma_f32_16x16x32_bf16 v[78:81], v[160:163], v[222:225], v[78:81]
	v_mfma_f32_16x16x32_bf16 v[74:77], v[174:177], v[222:225], v[74:77]
	v_mfma_f32_16x16x32_bf16 v[70:73], v[160:163], v[230:233], v[70:73]
	v_mfma_f32_16x16x32_bf16 v[66:69], v[174:177], v[230:233], v[66:69]
	v_mfma_f32_16x16x32_bf16 v[110:113], v[170:173], v[186:189], v[110:113]
	v_mfma_f32_16x16x32_bf16 v[106:109], v[178:181], v[186:189], v[106:109]
	v_mfma_f32_16x16x32_bf16 v[94:97], v[170:173], v[194:197], v[94:97]
	v_mfma_f32_16x16x32_bf16 v[90:93], v[178:181], v[194:197], v[90:93]
	v_mfma_f32_16x16x32_bf16 v[78:81], v[170:173], v[226:229], v[78:81]
	v_mfma_f32_16x16x32_bf16 v[74:77], v[178:181], v[226:229], v[74:77]
	v_mfma_f32_16x16x32_bf16 v[70:73], v[170:173], v[240:243], v[70:73]
	v_mfma_f32_16x16x32_bf16 v[66:69], v[178:181], v[240:243], v[66:69]
	s_setprio 0
	s_barrier
	s_add_i32 s37, s37, s22
	v_lshl_add_u64 v[204:205], s[2:3], 0, v[0:1]
	s_mov_b32 m0, s37
	ds_read_b128 v[182:185], v143 offset:16384
	ds_read_b128 v[186:189], v143 offset:17408
	ds_read_b128 v[190:193], v143 offset:18432
	ds_read_b128 v[194:197], v143 offset:19456
	ds_read_b128 v[222:225], v143 offset:20480
	ds_read_b128 v[226:229], v143 offset:21504
	ds_read_b128 v[230:233], v143 offset:22528
	ds_read_b128 v[240:243], v143 offset:23552
	global_load_lds_dwordx4 v[204:205], off
	s_add_i32 m0, s37, 0x2000
	s_add_u32 s40, s2, 0x200000
	v_lshl_add_u64 v[214:215], s[2:3], 0, v[130:131]
	s_addc_u32 s41, s3, 0
	s_add_i32 s37, s42, s22
	global_load_lds_dwordx4 v[214:215], off
	v_lshl_add_u64 v[234:235], s[40:41], 0, v[0:1]
	s_mov_b32 m0, s37
	v_lshl_add_u64 v[244:245], s[20:21], 0, v[132:133]
	global_load_lds_dwordx4 v[234:235], off
	v_lshl_add_u64 v[234:235], s[40:41], 0, v[130:131]
	s_add_i32 m0, s37, 0x2000
	s_nop 0
	global_load_lds_dwordx4 v[234:235], off
	v_lshl_add_u64 v[234:235], s[20:21], 0, v[134:135]
	s_mov_b32 m0, s23
	s_nop 0
	global_load_lds_dwordx4 v[234:235], off
	s_mov_b32 m0, s24
	s_nop 0
	global_load_lds_dwordx4 v[244:245], off
	s_waitcnt vmcnt(8)
	s_waitcnt lgkmcnt(0)
	s_barrier
; #define PG8_STAGE(bufoff, gbase, voff) do { _Pragma("unroll") for (int _i = 0; _i < 2; ++_i) \
;         __builtin_amdgcn_global_load_lds((const unsigned*)((const char*)(gbase) + (voff)[_i]), (PG8_LAS unsigned*)(lds + (bufoff) + ldsw + _i * 8192), 16, 0, 0); } while (0)
; #define PG8_LDA(dst, b, h) do { _Pragma("unroll") for (int m = 0; m < 4; ++m) _Pragma("unroll") for (int k = 0; k < 2; ++k) dst[m][k] = *(const PG8_LAS bf16x8*)(lds + PG8_SA(b, h) + aoff + m * 2048 + k * 1024); } while (0)
; #define PG8_LDB(dst, b, h) do { _Pragma("unroll") for (int n = 0; n < 2; ++n) _Pragma("unroll") for (int k = 0; k < 2; ++k) dst[n][k] = *(const PG8_LAS bf16x8*)(lds + PG8_SB(b, h) + boff + n * 2048 + k * 1024); } while (0)
; #define PG8_MMA(ai, bj, At, Bt) do { __builtin_amdgcn_s_setprio(1); _Pragma("unroll") for (int m = 0; m < 4; ++m) _Pragma("unroll") for (int n = 0; n < 2; ++n) _Pragma("unroll") for (int k = 0; k < 2; ++k) \
;         acc[ai][bj][m][n] = __builtin_amdgcn_mfma_f32_16x16x32_bf16(Bt[n][k], At[m][k], acc[ai][bj][m][n], 0, 0, 0); __builtin_amdgcn_s_setprio(0); } while (0)
; #define PG8_WAIT_V(n) asm volatile("s_waitcnt vmcnt(" #n ")" ::: "memory")
; #define PG8_WAIT_L(n) asm volatile("s_waitcnt lgkmcnt(" #n ")" ::: "memory")
; #define PG8_BAR __builtin_amdgcn_s_barrier()
; #define PG8_SCHED __builtin_amdgcn_sched_barrier(0)
; template <class Epi, class Sched, bool ALIGN_EPI = false, bool SP2 = false>
; __device__ __forceinline__ void gemm_phase(PG8_LAS unsigned char* lds, const Gemm g, const Sched& S, const Epi& E) {
;     ...
;             PG8_WAIT_V(8); PG8_WAIT_L(0); PG8_BAR; PG8_MMA(1, 0, At, B0); PG8_MMA(1, 1, At, B1); PG8_BAR; PG8_SCHED;
;             PG8_LDB(B0, 1, 0); PG8_LDB(B1, 1, 1); PG8_SCHED; PG8_LDA(At, 1, 0); PG8_STAGE(PG8_SA(0, 1), a2 + hstep, voffA);
;             PG8_WAIT_V(8); PG8_WAIT_L(0); PG8_BAR; PG8_MMA(0, 0, At, B0); PG8_MMA(0, 1, At, B1); PG8_BAR; PG8_SCHED;
	s_setprio 1
	s_waitcnt lgkmcnt(0)
	v_mfma_f32_16x16x32_bf16 v[62:65], v[144:147], v[182:185], v[62:65]
	v_mfma_f32_16x16x32_bf16 v[58:61], v[152:155], v[182:185], v[58:61]
	v_mfma_f32_16x16x32_bf16 v[54:57], v[144:147], v[190:193], v[54:57]
	v_mfma_f32_16x16x32_bf16 v[50:53], v[152:155], v[190:193], v[50:53]
	v_mfma_f32_16x16x32_bf16 v[38:41], v[144:147], v[222:225], v[38:41]
	v_mfma_f32_16x16x32_bf16 v[34:37], v[152:155], v[222:225], v[34:37]
	v_mfma_f32_16x16x32_bf16 v[22:25], v[144:147], v[230:233], v[22:25]
	v_mfma_f32_16x16x32_bf16 v[18:21], v[152:155], v[230:233], v[18:21]
	v_mfma_f32_16x16x32_bf16 v[62:65], v[148:151], v[186:189], v[62:65]
	v_mfma_f32_16x16x32_bf16 v[58:61], v[156:159], v[186:189], v[58:61]
	v_mfma_f32_16x16x32_bf16 v[54:57], v[148:151], v[194:197], v[54:57]
	v_mfma_f32_16x16x32_bf16 v[50:53], v[156:159], v[194:197], v[50:53]
	v_mfma_f32_16x16x32_bf16 v[38:41], v[148:151], v[226:229], v[38:41]
	v_mfma_f32_16x16x32_bf16 v[34:37], v[156:159], v[226:229], v[34:37]
	v_mfma_f32_16x16x32_bf16 v[22:25], v[148:151], v[240:243], v[22:25]
	v_mfma_f32_16x16x32_bf16 v[18:21], v[156:159], v[240:243], v[18:21]
	s_setprio 0
	s_setprio 1
	v_mfma_f32_16x16x32_bf16 v[46:49], v[160:163], v[182:185], v[46:49]
	v_mfma_f32_16x16x32_bf16 v[42:45], v[174:177], v[182:185], v[42:45]
	v_mfma_f32_16x16x32_bf16 v[30:33], v[160:163], v[190:193], v[30:33]
	v_mfma_f32_16x16x32_bf16 v[26:29], v[174:177], v[190:193], v[26:29]
	v_mfma_f32_16x16x32_bf16 v[14:17], v[160:163], v[222:225], v[14:17]
	v_mfma_f32_16x16x32_bf16 v[10:13], v[174:177], v[222:225], v[10:13]
	v_mfma_f32_16x16x32_bf16 v[6:9], v[160:163], v[230:233], v[6:9]
	v_mfma_f32_16x16x32_bf16 v[2:5], v[174:177], v[230:233], v[2:5]
	v_mfma_f32_16x16x32_bf16 v[46:49], v[170:173], v[186:189], v[46:49]
	v_mfma_f32_16x16x32_bf16 v[42:45], v[178:181], v[186:189], v[42:45]
	v_mfma_f32_16x16x32_bf16 v[30:33], v[170:173], v[194:197], v[30:33]
	v_mfma_f32_16x16x32_bf16 v[26:29], v[178:181], v[194:197], v[26:29]
	v_mfma_f32_16x16x32_bf16 v[14:17], v[170:173], v[226:229], v[14:17]
	v_mfma_f32_16x16x32_bf16 v[10:13], v[178:181], v[226:229], v[10:13]
	v_mfma_f32_16x16x32_bf16 v[6:9], v[170:173], v[240:243], v[6:9]
	v_mfma_f32_16x16x32_bf16 v[2:5], v[178:181], v[240:243], v[2:5]
	s_setprio 0
	s_barrier
	s_add_i32 s37, 0, 0x18000
	s_add_i32 s40, 0, 0x1c000
	v_add_u32_e32 v156, s37, v141
	v_add_u32_e32 v178, s40, v141
	ds_read_b128 v[144:147], v156
	ds_read_b128 v[148:151], v156 offset:1024
	ds_read_b128 v[152:155], v156 offset:2048
	ds_read_b128 v[156:159], v156 offset:3072
	ds_read_b128 v[160:163], v178
	ds_read_b128 v[170:173], v178 offset:1024
	ds_read_b128 v[174:177], v178 offset:2048
	ds_read_b128 v[178:181], v178 offset:3072
	s_add_u32 s20, s20, 0x200000
	s_addc_u32 s21, s21, 0
	s_mov_b32 m0, s25
	v_lshl_add_u64 v[246:247], s[20:21], 0, v[134:135]
	ds_read_b128 v[182:185], v143 offset:32768
	ds_read_b128 v[186:189], v143 offset:33792
	ds_read_b128 v[190:193], v143 offset:34816
	ds_read_b128 v[194:197], v143 offset:35840
	ds_read_b128 v[222:225], v143 offset:36864
	ds_read_b128 v[226:229], v143 offset:37888
	ds_read_b128 v[230:233], v143 offset:38912
	ds_read_b128 v[240:243], v143 offset:39936
	global_load_lds_dwordx4 v[246:247], off
	v_lshl_add_u64 v[246:247], s[20:21], 0, v[132:133]
	s_mov_b32 m0, s26
	s_nop 0
	global_load_lds_dwordx4 v[246:247], off
	s_waitcnt vmcnt(8)
	s_waitcnt lgkmcnt(0)
	s_barrier
	s_setprio 1
	s_waitcnt lgkmcnt(0)
	v_mfma_f32_16x16x32_bf16 v[126:129], v[144:147], v[182:185], v[126:129]
	v_mfma_f32_16x16x32_bf16 v[122:125], v[152:155], v[182:185], v[122:125]
	v_mfma_f32_16x16x32_bf16 v[118:121], v[144:147], v[190:193], v[118:121]
	v_mfma_f32_16x16x32_bf16 v[114:117], v[152:155], v[190:193], v[114:117]
	v_mfma_f32_16x16x32_bf16 v[102:105], v[144:147], v[222:225], v[102:105]
	v_mfma_f32_16x16x32_bf16 v[98:101], v[152:155], v[222:225], v[98:101]
	v_mfma_f32_16x16x32_bf16 v[86:89], v[144:147], v[230:233], v[86:89]
	v_mfma_f32_16x16x32_bf16 v[82:85], v[152:155], v[230:233], v[82:85]
	v_mfma_f32_16x16x32_bf16 v[126:129], v[148:151], v[186:189], v[126:129]
	v_mfma_f32_16x16x32_bf16 v[122:125], v[156:159], v[186:189], v[122:125]
	v_mfma_f32_16x16x32_bf16 v[118:121], v[148:151], v[194:197], v[118:121]
	v_mfma_f32_16x16x32_bf16 v[114:117], v[156:159], v[194:197], v[114:117]
	v_mfma_f32_16x16x32_bf16 v[102:105], v[148:151], v[226:229], v[102:105]
	v_mfma_f32_16x16x32_bf16 v[98:101], v[156:159], v[226:229], v[98:101]
	v_mfma_f32_16x16x32_bf16 v[86:89], v[148:151], v[240:243], v[86:89]
	v_mfma_f32_16x16x32_bf16 v[82:85], v[156:159], v[240:243], v[82:85]
	s_setprio 0
	s_setprio 1
	v_mfma_f32_16x16x32_bf16 v[110:113], v[160:163], v[182:185], v[110:113]
	v_mfma_f32_16x16x32_bf16 v[106:109], v[174:177], v[182:185], v[106:109]
	v_mfma_f32_16x16x32_bf16 v[94:97], v[160:163], v[190:193], v[94:97]
	v_mfma_f32_16x16x32_bf16 v[90:93], v[174:177], v[190:193], v[90:93]
	v_mfma_f32_16x16x32_bf16 v[78:81], v[160:163], v[222:225], v[78:81]
	v_mfma_f32_16x16x32_bf16 v[74:77], v[174:177], v[222:225], v[74:77]
	v_mfma_f32_16x16x32_bf16 v[70:73], v[160:163], v[230:233], v[70:73]
	v_mfma_f32_16x16x32_bf16 v[66:69], v[174:177], v[230:233], v[66:69]
	v_mfma_f32_16x16x32_bf16 v[110:113], v[170:173], v[186:189], v[110:113]
	v_mfma_f32_16x16x32_bf16 v[106:109], v[178:181], v[186:189], v[106:109]
	v_mfma_f32_16x16x32_bf16 v[94:97], v[170:173], v[194:197], v[94:97]
	v_mfma_f32_16x16x32_bf16 v[90:93], v[178:181], v[194:197], v[90:93]
	v_mfma_f32_16x16x32_bf16 v[78:81], v[170:173], v[226:229], v[78:81]
	v_mfma_f32_16x16x32_bf16 v[74:77], v[178:181], v[226:229], v[74:77]
	v_mfma_f32_16x16x32_bf16 v[70:73], v[170:173], v[240:243], v[70:73]
	v_mfma_f32_16x16x32_bf16 v[66:69], v[178:181], v[240:243], v[66:69]
	s_setprio 0
	s_barrier
; #define PG8_STAGE(bufoff, gbase, voff) do { _Pragma("unroll") for (int _i = 0; _i < 2; ++_i) \
;         __builtin_amdgcn_global_load_lds((const unsigned*)((const char*)(gbase) + (voff)[_i]), (PG8_LAS unsigned*)(lds + (bufoff) + ldsw + _i * 8192), 16, 0, 0); } while (0)
; #define PG8_LDA(dst, b, h) do { _Pragma("unroll") for (int m = 0; m < 4; ++m) _Pragma("unroll") for (int k = 0; k < 2; ++k) dst[m][k] = *(const PG8_LAS bf16x8*)(lds + PG8_SA(b, h) + aoff + m * 2048 + k * 1024); } while (0)
; #define PG8_MMA(ai, bj, At, Bt) do { __builtin_amdgcn_s_setprio(1); _Pragma("unroll") for (int m = 0; m < 4; ++m) _Pragma("unroll") for (int n = 0; n < 2; ++n) _Pragma("unroll") for (int k = 0; k < 2; ++k) \
;         acc[ai][bj][m][n] = __builtin_amdgcn_mfma_f32_16x16x32_bf16(Bt[n][k], At[m][k], acc[ai][bj][m][n], 0, 0, 0); __builtin_amdgcn_s_setprio(0); } while (0)
; #define PG8_WAIT_V(n) asm volatile("s_waitcnt vmcnt(" #n ")" ::: "memory")
; #define PG8_WAIT_L(n) asm volatile("s_waitcnt lgkmcnt(" #n ")" ::: "memory")
; #define PG8_BAR __builtin_amdgcn_s_barrier()
; #define PG8_SCHED __builtin_amdgcn_sched_barrier(0)
; template <class Epi, class Sched, bool ALIGN_EPI = false, bool SP2 = false>
; __device__ __forceinline__ void gemm_phase(PG8_LAS unsigned char* lds, const Gemm g, const Sched& S, const Epi& E) {
;     ...
;             PG8_LDA(At, 1, 1); PG8_STAGE(PG8_SB(1, 0), b3, voffB); PG8_STAGE(PG8_SB(1, 1), b3 + hstep, voffB); PG8_STAGE(PG8_SA(1, 0), a3, voffA);
;             PG8_WAIT_V(8); PG8_WAIT_L(0); PG8_BAR; PG8_MMA(1, 0, At, B0); PG8_MMA(1, 1, At, B1); PG8_BAR; PG8_SCHED;
	s_add_i32 s20, s37, s22
	v_lshl_add_u64 v[204:205], v[204:205], 0, s[48:49]
	s_mov_b32 m0, s20
	ds_read_b128 v[182:185], v143 offset:49152
	ds_read_b128 v[186:189], v143 offset:50176
	ds_read_b128 v[190:193], v143 offset:51200
	ds_read_b128 v[194:197], v143 offset:52224
	ds_read_b128 v[222:225], v143 offset:53248
	ds_read_b128 v[226:229], v143 offset:54272
	ds_read_b128 v[230:233], v143 offset:55296
	ds_read_b128 v[240:243], v143 offset:56320
	global_load_lds_dwordx4 v[204:205], off
	s_add_i32 m0, s20, 0x2000
	s_add_u32 s2, s2, 0x200080
	v_lshl_add_u64 v[204:205], v[214:215], 0, s[48:49]
	s_addc_u32 s3, s3, 0
	s_add_i32 s20, s40, s22
	global_load_lds_dwordx4 v[204:205], off
	v_lshl_add_u64 v[204:205], s[2:3], 0, v[0:1]
	s_mov_b32 m0, s20
	s_nop 0
	global_load_lds_dwordx4 v[204:205], off
	v_lshl_add_u64 v[204:205], s[2:3], 0, v[130:131]
	s_add_i32 m0, s20, 0x2000
	s_nop 0
	global_load_lds_dwordx4 v[204:205], off
	v_lshl_add_u64 v[204:205], v[234:235], 0, s[48:49]
	s_mov_b32 m0, s27
	s_nop 0
	global_load_lds_dwordx4 v[204:205], off
	v_lshl_add_u64 v[204:205], v[244:245], 0, s[48:49]
	s_mov_b32 m0, s28
	s_nop 0
	global_load_lds_dwordx4 v[204:205], off
	s_waitcnt vmcnt(8)
	s_waitcnt lgkmcnt(0)
	s_barrier
	s_setprio 1
	s_waitcnt lgkmcnt(0)
	v_mfma_f32_16x16x32_bf16 v[62:65], v[144:147], v[182:185], v[62:65]
	v_mfma_f32_16x16x32_bf16 v[58:61], v[152:155], v[182:185], v[58:61]
	v_mfma_f32_16x16x32_bf16 v[54:57], v[144:147], v[190:193], v[54:57]
	v_mfma_f32_16x16x32_bf16 v[50:53], v[152:155], v[190:193], v[50:53]
	v_mfma_f32_16x16x32_bf16 v[38:41], v[144:147], v[222:225], v[38:41]
	v_mfma_f32_16x16x32_bf16 v[34:37], v[152:155], v[222:225], v[34:37]
	v_mfma_f32_16x16x32_bf16 v[22:25], v[144:147], v[230:233], v[22:25]
	v_mfma_f32_16x16x32_bf16 v[18:21], v[152:155], v[230:233], v[18:21]
	v_mfma_f32_16x16x32_bf16 v[62:65], v[148:151], v[186:189], v[62:65]
	v_mfma_f32_16x16x32_bf16 v[58:61], v[156:159], v[186:189], v[58:61]
	v_mfma_f32_16x16x32_bf16 v[54:57], v[148:151], v[194:197], v[54:57]
	v_mfma_f32_16x16x32_bf16 v[50:53], v[156:159], v[194:197], v[50:53]
	v_mfma_f32_16x16x32_bf16 v[38:41], v[148:151], v[226:229], v[38:41]
	v_mfma_f32_16x16x32_bf16 v[34:37], v[156:159], v[226:229], v[34:37]
	v_mfma_f32_16x16x32_bf16 v[22:25], v[148:151], v[240:243], v[22:25]
	v_mfma_f32_16x16x32_bf16 v[18:21], v[156:159], v[240:243], v[18:21]
	s_setprio 0
	s_setprio 1
	v_mfma_f32_16x16x32_bf16 v[46:49], v[160:163], v[182:185], v[46:49]
	v_mfma_f32_16x16x32_bf16 v[42:45], v[174:177], v[182:185], v[42:45]
	v_mfma_f32_16x16x32_bf16 v[30:33], v[160:163], v[190:193], v[30:33]
	v_mfma_f32_16x16x32_bf16 v[26:29], v[174:177], v[190:193], v[26:29]
	v_mfma_f32_16x16x32_bf16 v[14:17], v[160:163], v[222:225], v[14:17]
	v_mfma_f32_16x16x32_bf16 v[10:13], v[174:177], v[222:225], v[10:13]
	v_mfma_f32_16x16x32_bf16 v[6:9], v[160:163], v[230:233], v[6:9]
	v_mfma_f32_16x16x32_bf16 v[2:5], v[174:177], v[230:233], v[2:5]
	v_mfma_f32_16x16x32_bf16 v[46:49], v[170:173], v[186:189], v[46:49]
	v_mfma_f32_16x16x32_bf16 v[42:45], v[178:181], v[186:189], v[42:45]
	v_mfma_f32_16x16x32_bf16 v[30:33], v[170:173], v[194:197], v[30:33]
	v_mfma_f32_16x16x32_bf16 v[26:29], v[178:181], v[194:197], v[26:29]
	v_mfma_f32_16x16x32_bf16 v[14:17], v[170:173], v[226:229], v[14:17]
	v_mfma_f32_16x16x32_bf16 v[10:13], v[178:181], v[226:229], v[10:13]
	v_mfma_f32_16x16x32_bf16 v[6:9], v[170:173], v[240:243], v[6:9]
	v_mfma_f32_16x16x32_bf16 v[2:5], v[178:181], v[240:243], v[2:5]
	s_setprio 0
	s_add_i32 s36, s36, 2
	s_add_u32 s18, s18, 0x100
	s_addc_u32 s19, s19, 0
	s_add_u32 s34, s34, 0x100
	s_addc_u32 s35, s35, 0
	s_cmp_gt_u32 s36, 29
	s_barrier
	s_cbranch_scc0 .LBB0_1550
	s_and_b64 vcc, exec, s[4:5]
	s_cbranch_vccz .LBB0_1553
	s_barrier
